# GEMM K-loops: 12-13 of 16 LDS-DMA per iteration use SGPR-base form (chained +0x80 addresses via 2 SALU into vcc); 3-4 v_lshl_add_u64 left per iteration
# baseline (speedup 1.0000x reference)
; #define PG8_STAGE(bufoff, gbase, voff) do { _Pragma("unroll") for (int _i = 0; _i < 2; ++_i) \
;         __builtin_amdgcn_global_load_lds((const unsigned*)((const char*)(gbase) + (voff)[_i]), (PG8_LAS unsigned*)(lds + (bufoff) + ldsw + _i * 8192), 16, 0, 0); } while (0)
; #define PG8_LDA(dst, b, h) do { _Pragma("unroll") for (int m = 0; m < 4; ++m) _Pragma("unroll") for (int k = 0; k < 2; ++k) dst[m][k] = *(const PG8_LAS bf16x8*)(lds + PG8_SA(b, h) + aoff + m * 2048 + k * 1024); } while (0)
; #define PG8_LDB(dst, b, h) do { _Pragma("unroll") for (int n = 0; n < 2; ++n) _Pragma("unroll") for (int k = 0; k < 2; ++k) dst[n][k] = *(const PG8_LAS bf16x8*)(lds + PG8_SB(b, h) + boff + n * 2048 + k * 1024); } while (0)
; #define PG8_MMA(ai, bj, At, Bt) do { __builtin_amdgcn_s_setprio(1); _Pragma("unroll") for (int m = 0; m < 4; ++m) _Pragma("unroll") for (int n = 0; n < 2; ++n) _Pragma("unroll") for (int k = 0; k < 2; ++k) \
;         acc[ai][bj][m][n] = __builtin_amdgcn_mfma_f32_16x16x32_bf16(Bt[n][k], At[m][k], acc[ai][bj][m][n], 0, 0, 0); __builtin_amdgcn_s_setprio(0); } while (0)
; #define PG8_WAIT_V(n) asm volatile("s_waitcnt vmcnt(" #n ")" ::: "memory")
; #define PG8_WAIT_L(n) asm volatile("s_waitcnt lgkmcnt(" #n ")" ::: "memory")
; template <class Epi, class Sched, bool ALIGN_EPI = false, bool SP2 = false>
; __device__ __forceinline__ void gemm_phase(PG8_LAS unsigned char* lds, const Gemm g, const Sched& S, const Epi& E) {
;     ...
;             const bool last = (t == nt - 2);
;             const char* a1 = cA + (size_t)(t + 1) * kstep;
;             const char* a2 = last ? nA : cA + (size_t)(t + 2) * kstep; const char* b2 = last ? nB : cB + (size_t)(t + 2) * kstep;
;             const char* a3 = a2 + kstep; const char* b3 = b2 + kstep;
;             if (last && has_next) S.a_ready(nxt);
;             if constexpr (SP2) {
;             PG8_LDB(B0, 0, 0); PG8_LDB(B1, 0, 1); PG8_SCHED; PG8_LDA(At, 0, 0); PG8_STAGE(PG8_SA(1, 1), a1 + hstep, voffA);
;             PG8_WAIT_V(8); PG8_WAIT_L(0); PG8_BAR; PG8_MMA(0, 0, At, B0); PG8_MMA(0, 1, At, B1); PG8_BAR; PG8_SCHED;
;             PG8_LDA(At, 0, 1); PG8_STAGE(PG8_SB(0, 0), b2, voffB); PG8_STAGE(PG8_SB(0, 1), b2 + hstep, voffB); PG8_STAGE(PG8_SA(0, 0), a2, voffA);
;             PG8_WAIT_V(8); PG8_WAIT_L(0); PG8_BAR; PG8_MMA(1, 0, At, B0); PG8_MMA(1, 1, At, B1); PG8_BAR; PG8_SCHED;
.LBB0_85:
	s_add_u32 s20, s18, 0xfff80080
	s_addc_u32 s21, s19, -1
	s_add_i32 s56, 0, 0x10000
	s_cmp_eq_u32 s51, 28
	s_cselect_b32 s23, s11, s21
	s_cselect_b32 s22, s42, s20
	v_add_u32_e32 v150, s56, v153
	s_cselect_b32 s21, s9, s50
	s_cselect_b32 s20, s44, s45
	s_add_i32 s63, 0, 0x14000
	ds_read_b128 v[184:187], v150
	ds_read_b128 v[188:191], v150 offset:1024
	ds_read_b128 v[192:195], v150 offset:2048
	ds_read_b128 v[196:199], v150 offset:3072
	v_add_u32_e32 v150, s63, v153
	ds_read_b128 v[200:203], v150
	ds_read_b128 v[204:207], v150 offset:1024
	ds_read_b128 v[208:211], v150 offset:2048
	ds_read_b128 v[212:215], v150 offset:3072
	s_add_i32 m0, s27, 0xc000
	ds_read_b128 v[216:219], v155
	ds_read_b128 v[220:223], v155 offset:1024
	ds_read_b128 v[224:227], v155 offset:2048
	ds_read_b128 v[228:231], v155 offset:3072
	ds_read_b128 v[232:235], v155 offset:4096
	ds_read_b128 v[236:239], v155 offset:5120
	ds_read_b128 v[240:243], v155 offset:6144
	ds_read_b128 v[244:247], v155 offset:7168
	global_load_lds_dwordx4 v136, s[18:19]
	s_add_i32 m0, s27, 0xe000
	s_nop 0
	global_load_lds_dwordx4 v138, s[18:19]
	s_waitcnt vmcnt(8)
	s_waitcnt lgkmcnt(0)
	s_barrier
	s_setprio 1
	s_waitcnt lgkmcnt(0)
	v_mfma_f32_16x16x32_bf16 v[128:131], v[184:187], v[216:219], v[128:131]
	v_mfma_f32_16x16x32_bf16 v[120:123], v[192:195], v[216:219], v[120:123]
	v_mfma_f32_16x16x32_bf16 v[112:115], v[184:187], v[224:227], v[112:115]
	v_mfma_f32_16x16x32_bf16 v[104:107], v[192:195], v[224:227], v[104:107]
	v_mfma_f32_16x16x32_bf16 v[96:99], v[184:187], v[232:235], v[96:99]
	v_mfma_f32_16x16x32_bf16 v[88:91], v[192:195], v[232:235], v[88:91]
	v_mfma_f32_16x16x32_bf16 v[80:83], v[184:187], v[240:243], v[80:83]
	v_mfma_f32_16x16x32_bf16 v[72:75], v[192:195], v[240:243], v[72:75]
	v_mfma_f32_16x16x32_bf16 v[128:131], v[188:191], v[220:223], v[128:131]
	v_mfma_f32_16x16x32_bf16 v[120:123], v[196:199], v[220:223], v[120:123]
	v_mfma_f32_16x16x32_bf16 v[112:115], v[188:191], v[228:231], v[112:115]
	v_mfma_f32_16x16x32_bf16 v[104:107], v[196:199], v[228:231], v[104:107]
	v_mfma_f32_16x16x32_bf16 v[96:99], v[188:191], v[236:239], v[96:99]
	v_mfma_f32_16x16x32_bf16 v[88:91], v[196:199], v[236:239], v[88:91]
	v_mfma_f32_16x16x32_bf16 v[80:83], v[188:191], v[244:247], v[80:83]
	v_mfma_f32_16x16x32_bf16 v[72:75], v[196:199], v[244:247], v[72:75]
	s_setprio 0
	s_setprio 1
	v_mfma_f32_16x16x32_bf16 v[124:127], v[200:203], v[216:219], v[124:127]
	v_mfma_f32_16x16x32_bf16 v[116:119], v[208:211], v[216:219], v[116:119]
	v_mfma_f32_16x16x32_bf16 v[108:111], v[200:203], v[224:227], v[108:111]
	v_mfma_f32_16x16x32_bf16 v[100:103], v[208:211], v[224:227], v[100:103]
	v_mfma_f32_16x16x32_bf16 v[92:95], v[200:203], v[232:235], v[92:95]
	v_mfma_f32_16x16x32_bf16 v[84:87], v[208:211], v[232:235], v[84:87]
	v_mfma_f32_16x16x32_bf16 v[76:79], v[200:203], v[240:243], v[76:79]
	v_mfma_f32_16x16x32_bf16 v[68:71], v[208:211], v[240:243], v[68:71]
	v_mfma_f32_16x16x32_bf16 v[124:127], v[204:207], v[220:223], v[124:127]
	v_mfma_f32_16x16x32_bf16 v[116:119], v[212:215], v[220:223], v[116:119]
	v_mfma_f32_16x16x32_bf16 v[108:111], v[204:207], v[228:231], v[108:111]
	v_mfma_f32_16x16x32_bf16 v[100:103], v[212:215], v[228:231], v[100:103]
	v_mfma_f32_16x16x32_bf16 v[92:95], v[204:207], v[236:239], v[92:95]
	v_mfma_f32_16x16x32_bf16 v[84:87], v[212:215], v[236:239], v[84:87]
	v_mfma_f32_16x16x32_bf16 v[76:79], v[204:207], v[244:247], v[76:79]
	v_mfma_f32_16x16x32_bf16 v[68:71], v[212:215], v[244:247], v[68:71]
	s_setprio 0
	s_barrier
	s_add_i32 s56, s56, s25
	s_mov_b32 m0, s56
	ds_read_b128 v[216:219], v155 offset:16384
	ds_read_b128 v[220:223], v155 offset:17408
	ds_read_b128 v[224:227], v155 offset:18432
	ds_read_b128 v[228:231], v155 offset:19456
	ds_read_b128 v[232:235], v155 offset:20480
	ds_read_b128 v[236:239], v155 offset:21504
	ds_read_b128 v[240:243], v155 offset:22528
	ds_read_b128 v[244:247], v155 offset:23552
	global_load_lds_dwordx4 v2, s[20:21]
	s_add_i32 m0, s56, 0x2000
	s_add_u32 s56, s20, 0x80000
	s_addc_u32 s57, s21, 0
	s_add_i32 s63, s63, s25
	global_load_lds_dwordx4 v0, s[20:21]
	s_mov_b32 m0, s63
	v_lshl_add_u64 v[252:253], s[22:23], 0, v[132:133]
	global_load_lds_dwordx4 v2, s[56:57]
	s_add_i32 m0, s63, 0x2000
	s_nop 0
	global_load_lds_dwordx4 v0, s[56:57]
	v_lshl_add_u64 v[250:251], s[22:23], 0, v[134:135]
	s_mov_b32 m0, s27
	s_nop 0
	global_load_lds_dwordx4 v[250:251], off
	s_mov_b32 m0, s28
	s_nop 0
	global_load_lds_dwordx4 v[252:253], off
	s_waitcnt vmcnt(8)
	s_waitcnt lgkmcnt(0)
	s_barrier
; #define PG8_STAGE(bufoff, gbase, voff) do { _Pragma("unroll") for (int _i = 0; _i < 2; ++_i) \
;         __builtin_amdgcn_global_load_lds((const unsigned*)((const char*)(gbase) + (voff)[_i]), (PG8_LAS unsigned*)(lds + (bufoff) + ldsw + _i * 8192), 16, 0, 0); } while (0)
; #define PG8_LDA(dst, b, h) do { _Pragma("unroll") for (int m = 0; m < 4; ++m) _Pragma("unroll") for (int k = 0; k < 2; ++k) dst[m][k] = *(const PG8_LAS bf16x8*)(lds + PG8_SA(b, h) + aoff + m * 2048 + k * 1024); } while (0)
; #define PG8_LDB(dst, b, h) do { _Pragma("unroll") for (int n = 0; n < 2; ++n) _Pragma("unroll") for (int k = 0; k < 2; ++k) dst[n][k] = *(const PG8_LAS bf16x8*)(lds + PG8_SB(b, h) + boff + n * 2048 + k * 1024); } while (0)
; #define PG8_MMA(ai, bj, At, Bt) do { __builtin_amdgcn_s_setprio(1); _Pragma("unroll") for (int m = 0; m < 4; ++m) _Pragma("unroll") for (int n = 0; n < 2; ++n) _Pragma("unroll") for (int k = 0; k < 2; ++k) \
;         acc[ai][bj][m][n] = __builtin_amdgcn_mfma_f32_16x16x32_bf16(Bt[n][k], At[m][k], acc[ai][bj][m][n], 0, 0, 0); __builtin_amdgcn_s_setprio(0); } while (0)
; #define PG8_WAIT_V(n) asm volatile("s_waitcnt vmcnt(" #n ")" ::: "memory")
; #define PG8_WAIT_L(n) asm volatile("s_waitcnt lgkmcnt(" #n ")" ::: "memory")
; #define PG8_BAR __builtin_amdgcn_s_barrier()
; #define PG8_SCHED __builtin_amdgcn_sched_barrier(0)
; template <class Epi, class Sched, bool ALIGN_EPI = false, bool SP2 = false>
; __device__ __forceinline__ void gemm_phase(PG8_LAS unsigned char* lds, const Gemm g, const Sched& S, const Epi& E) {
;     ...
;             PG8_WAIT_V(8); PG8_WAIT_L(0); PG8_BAR; PG8_MMA(1, 0, At, B0); PG8_MMA(1, 1, At, B1); PG8_BAR; PG8_SCHED;
;             PG8_LDB(B0, 1, 0); PG8_LDB(B1, 1, 1); PG8_SCHED; PG8_LDA(At, 1, 0); PG8_STAGE(PG8_SA(0, 1), a2 + hstep, voffA);
;             PG8_WAIT_V(8); PG8_WAIT_L(0); PG8_BAR; PG8_MMA(0, 0, At, B0); PG8_MMA(0, 1, At, B1); PG8_BAR; PG8_SCHED;
	s_setprio 1
	s_waitcnt lgkmcnt(0)
	v_mfma_f32_16x16x32_bf16 v[64:67], v[184:187], v[216:219], v[64:67]
	v_mfma_f32_16x16x32_bf16 v[56:59], v[192:195], v[216:219], v[56:59]
	v_mfma_f32_16x16x32_bf16 v[48:51], v[184:187], v[224:227], v[48:51]
	v_mfma_f32_16x16x32_bf16 v[40:43], v[192:195], v[224:227], v[40:43]
	v_mfma_f32_16x16x32_bf16 v[32:35], v[184:187], v[232:235], v[32:35]
	v_mfma_f32_16x16x32_bf16 v[24:27], v[192:195], v[232:235], v[24:27]
	v_mfma_f32_16x16x32_bf16 v[16:19], v[184:187], v[240:243], v[16:19]
	v_mfma_f32_16x16x32_bf16 v[8:11], v[192:195], v[240:243], v[8:11]
	v_mfma_f32_16x16x32_bf16 v[64:67], v[188:191], v[220:223], v[64:67]
	v_mfma_f32_16x16x32_bf16 v[56:59], v[196:199], v[220:223], v[56:59]
	v_mfma_f32_16x16x32_bf16 v[48:51], v[188:191], v[228:231], v[48:51]
	v_mfma_f32_16x16x32_bf16 v[40:43], v[196:199], v[228:231], v[40:43]
	v_mfma_f32_16x16x32_bf16 v[32:35], v[188:191], v[236:239], v[32:35]
	v_mfma_f32_16x16x32_bf16 v[24:27], v[196:199], v[236:239], v[24:27]
	v_mfma_f32_16x16x32_bf16 v[16:19], v[188:191], v[244:247], v[16:19]
	v_mfma_f32_16x16x32_bf16 v[8:11], v[196:199], v[244:247], v[8:11]
	s_setprio 0
	s_setprio 1
	v_mfma_f32_16x16x32_bf16 v[60:63], v[200:203], v[216:219], v[60:63]
	v_mfma_f32_16x16x32_bf16 v[52:55], v[208:211], v[216:219], v[52:55]
	v_mfma_f32_16x16x32_bf16 v[44:47], v[200:203], v[224:227], v[44:47]
	v_mfma_f32_16x16x32_bf16 v[36:39], v[208:211], v[224:227], v[36:39]
	v_mfma_f32_16x16x32_bf16 v[28:31], v[200:203], v[232:235], v[28:31]
	v_mfma_f32_16x16x32_bf16 v[20:23], v[208:211], v[232:235], v[20:23]
	v_mfma_f32_16x16x32_bf16 v[12:15], v[200:203], v[240:243], v[12:15]
	v_mfma_f32_16x16x32_bf16 v[4:7], v[208:211], v[240:243], v[4:7]
	v_mfma_f32_16x16x32_bf16 v[60:63], v[204:207], v[220:223], v[60:63]
	v_mfma_f32_16x16x32_bf16 v[52:55], v[212:215], v[220:223], v[52:55]
	v_mfma_f32_16x16x32_bf16 v[44:47], v[204:207], v[228:231], v[44:47]
	v_mfma_f32_16x16x32_bf16 v[36:39], v[212:215], v[228:231], v[36:39]
	v_mfma_f32_16x16x32_bf16 v[28:31], v[204:207], v[236:239], v[28:31]
	v_mfma_f32_16x16x32_bf16 v[20:23], v[212:215], v[236:239], v[20:23]
	v_mfma_f32_16x16x32_bf16 v[12:15], v[204:207], v[244:247], v[12:15]
	v_mfma_f32_16x16x32_bf16 v[4:7], v[212:215], v[244:247], v[4:7]
	s_setprio 0
	s_barrier
	s_add_i32 s56, 0, 0x18000
	v_add_u32_e32 v161, s56, v153
	s_add_i32 s57, 0, 0x1c000
	ds_read_b128 v[184:187], v161
	ds_read_b128 v[188:191], v161 offset:1024
	ds_read_b128 v[192:195], v161 offset:2048
	ds_read_b128 v[196:199], v161 offset:3072
	v_add_u32_e32 v161, s57, v153
	ds_read_b128 v[200:203], v161
	ds_read_b128 v[204:207], v161 offset:1024
	ds_read_b128 v[208:211], v161 offset:2048
	ds_read_b128 v[212:215], v161 offset:3072
	s_add_u32 s22, s22, 0x80000
	s_addc_u32 s23, s23, 0
	s_mov_b32 m0, s29
	ds_read_b128 v[216:219], v155 offset:32768
	ds_read_b128 v[220:223], v155 offset:33792
	ds_read_b128 v[224:227], v155 offset:34816
	ds_read_b128 v[228:231], v155 offset:35840
	ds_read_b128 v[232:235], v155 offset:36864
	ds_read_b128 v[236:239], v155 offset:37888
	ds_read_b128 v[240:243], v155 offset:38912
	ds_read_b128 v[244:247], v155 offset:39936
	global_load_lds_dwordx4 v134, s[22:23]
	s_mov_b32 m0, s30
	s_nop 0
	global_load_lds_dwordx4 v132, s[22:23]
	s_waitcnt vmcnt(8)
	s_waitcnt lgkmcnt(0)
	s_barrier
	s_setprio 1
	s_waitcnt lgkmcnt(0)
	v_mfma_f32_16x16x32_bf16 v[128:131], v[184:187], v[216:219], v[128:131]
	v_mfma_f32_16x16x32_bf16 v[120:123], v[192:195], v[216:219], v[120:123]
	v_mfma_f32_16x16x32_bf16 v[112:115], v[184:187], v[224:227], v[112:115]
	v_mfma_f32_16x16x32_bf16 v[104:107], v[192:195], v[224:227], v[104:107]
	v_mfma_f32_16x16x32_bf16 v[96:99], v[184:187], v[232:235], v[96:99]
	v_mfma_f32_16x16x32_bf16 v[88:91], v[192:195], v[232:235], v[88:91]
	v_mfma_f32_16x16x32_bf16 v[80:83], v[184:187], v[240:243], v[80:83]
	v_mfma_f32_16x16x32_bf16 v[72:75], v[192:195], v[240:243], v[72:75]
	v_mfma_f32_16x16x32_bf16 v[128:131], v[188:191], v[220:223], v[128:131]
	v_mfma_f32_16x16x32_bf16 v[120:123], v[196:199], v[220:223], v[120:123]
	v_mfma_f32_16x16x32_bf16 v[112:115], v[188:191], v[228:231], v[112:115]
	v_mfma_f32_16x16x32_bf16 v[104:107], v[196:199], v[228:231], v[104:107]
	v_mfma_f32_16x16x32_bf16 v[96:99], v[188:191], v[236:239], v[96:99]
	v_mfma_f32_16x16x32_bf16 v[88:91], v[196:199], v[236:239], v[88:91]
	v_mfma_f32_16x16x32_bf16 v[80:83], v[188:191], v[244:247], v[80:83]
	v_mfma_f32_16x16x32_bf16 v[72:75], v[196:199], v[244:247], v[72:75]
	s_setprio 0
	s_setprio 1
	v_mfma_f32_16x16x32_bf16 v[124:127], v[200:203], v[216:219], v[124:127]
	v_mfma_f32_16x16x32_bf16 v[116:119], v[208:211], v[216:219], v[116:119]
	v_mfma_f32_16x16x32_bf16 v[108:111], v[200:203], v[224:227], v[108:111]
	v_mfma_f32_16x16x32_bf16 v[100:103], v[208:211], v[224:227], v[100:103]
	v_mfma_f32_16x16x32_bf16 v[92:95], v[200:203], v[232:235], v[92:95]
	v_mfma_f32_16x16x32_bf16 v[84:87], v[208:211], v[232:235], v[84:87]
	v_mfma_f32_16x16x32_bf16 v[76:79], v[200:203], v[240:243], v[76:79]
	v_mfma_f32_16x16x32_bf16 v[68:71], v[208:211], v[240:243], v[68:71]
	v_mfma_f32_16x16x32_bf16 v[124:127], v[204:207], v[220:223], v[124:127]
	v_mfma_f32_16x16x32_bf16 v[116:119], v[212:215], v[220:223], v[116:119]
	v_mfma_f32_16x16x32_bf16 v[108:111], v[204:207], v[228:231], v[108:111]
	v_mfma_f32_16x16x32_bf16 v[100:103], v[212:215], v[228:231], v[100:103]
	v_mfma_f32_16x16x32_bf16 v[92:95], v[204:207], v[236:239], v[92:95]
	v_mfma_f32_16x16x32_bf16 v[84:87], v[212:215], v[236:239], v[84:87]
	v_mfma_f32_16x16x32_bf16 v[76:79], v[204:207], v[244:247], v[76:79]
	v_mfma_f32_16x16x32_bf16 v[68:71], v[212:215], v[244:247], v[68:71]
	s_setprio 0
	s_barrier
; #define PG8_STAGE(bufoff, gbase, voff) do { _Pragma("unroll") for (int _i = 0; _i < 2; ++_i) \
;         __builtin_amdgcn_global_load_lds((const unsigned*)((const char*)(gbase) + (voff)[_i]), (PG8_LAS unsigned*)(lds + (bufoff) + ldsw + _i * 8192), 16, 0, 0); } while (0)
; #define PG8_LDA(dst, b, h) do { _Pragma("unroll") for (int m = 0; m < 4; ++m) _Pragma("unroll") for (int k = 0; k < 2; ++k) dst[m][k] = *(const PG8_LAS bf16x8*)(lds + PG8_SA(b, h) + aoff + m * 2048 + k * 1024); } while (0)
; #define PG8_MMA(ai, bj, At, Bt) do { __builtin_amdgcn_s_setprio(1); _Pragma("unroll") for (int m = 0; m < 4; ++m) _Pragma("unroll") for (int n = 0; n < 2; ++n) _Pragma("unroll") for (int k = 0; k < 2; ++k) \
;         acc[ai][bj][m][n] = __builtin_amdgcn_mfma_f32_16x16x32_bf16(Bt[n][k], At[m][k], acc[ai][bj][m][n], 0, 0, 0); __builtin_amdgcn_s_setprio(0); } while (0)
; #define PG8_WAIT_V(n) asm volatile("s_waitcnt vmcnt(" #n ")" ::: "memory")
; #define PG8_WAIT_L(n) asm volatile("s_waitcnt lgkmcnt(" #n ")" ::: "memory")
; #define PG8_BAR __builtin_amdgcn_s_barrier()
; #define PG8_SCHED __builtin_amdgcn_sched_barrier(0)
; template <class Epi, class Sched, bool ALIGN_EPI = false, bool SP2 = false>
; __device__ __forceinline__ void gemm_phase(PG8_LAS unsigned char* lds, const Gemm g, const Sched& S, const Epi& E) {
;     ...
;             PG8_LDA(At, 1, 1); PG8_STAGE(PG8_SB(1, 0), b3, voffB); PG8_STAGE(PG8_SB(1, 1), b3 + hstep, voffB); PG8_STAGE(PG8_SA(1, 0), a3, voffA);
;             PG8_WAIT_V(8); PG8_WAIT_L(0); PG8_BAR; PG8_MMA(1, 0, At, B0); PG8_MMA(1, 1, At, B1); PG8_BAR; PG8_SCHED;
;     ...
;         if constexpr (ALIGN_EPI) { if (wr == 0) PG8_BAR; }
	s_add_i32 s22, s56, s25
	s_mov_b32 m0, s22
	ds_read_b128 v[216:219], v155 offset:49152
	ds_read_b128 v[220:223], v155 offset:50176
	ds_read_b128 v[224:227], v155 offset:51200
	ds_read_b128 v[228:231], v155 offset:52224
	ds_read_b128 v[232:235], v155 offset:53248
	ds_read_b128 v[236:239], v155 offset:54272
	ds_read_b128 v[240:243], v155 offset:55296
	ds_read_b128 v[244:247], v155 offset:56320
	s_add_u32 vcc_lo, s20, 0x80
	s_addc_u32 vcc_hi, s21, 0
	global_load_lds_dwordx4 v2, vcc
	s_add_i32 m0, s22, 0x2000
	s_add_u32 s20, s20, 0x80080
	s_addc_u32 s21, s21, 0
	s_add_i32 s22, s57, s25
	s_add_u32 vcc_lo, s20, 0xfff80000
	s_addc_u32 vcc_hi, s21, -1
	global_load_lds_dwordx4 v0, vcc
	s_mov_b32 m0, s22
	s_nop 0
	global_load_lds_dwordx4 v2, s[20:21]
	s_add_i32 m0, s22, 0x2000
	s_nop 0
	global_load_lds_dwordx4 v0, s[20:21]
	v_lshl_add_u64 v[150:151], v[250:251], 0, s[36:37]
	s_mov_b32 m0, s31
	s_nop 0
	global_load_lds_dwordx4 v[150:151], off
	v_lshl_add_u64 v[150:151], v[252:253], 0, s[36:37]
	s_mov_b32 m0, s34
	s_nop 0
	global_load_lds_dwordx4 v[150:151], off
	s_waitcnt vmcnt(8)
	s_waitcnt lgkmcnt(0)
	s_barrier
	s_setprio 1
	s_waitcnt lgkmcnt(0)
	v_mfma_f32_16x16x32_bf16 v[64:67], v[184:187], v[216:219], v[64:67]
	v_mfma_f32_16x16x32_bf16 v[56:59], v[192:195], v[216:219], v[56:59]
	v_mfma_f32_16x16x32_bf16 v[48:51], v[184:187], v[224:227], v[48:51]
	v_mfma_f32_16x16x32_bf16 v[40:43], v[192:195], v[224:227], v[40:43]
	v_mfma_f32_16x16x32_bf16 v[32:35], v[184:187], v[232:235], v[32:35]
	v_mfma_f32_16x16x32_bf16 v[24:27], v[192:195], v[232:235], v[24:27]
	v_mfma_f32_16x16x32_bf16 v[16:19], v[184:187], v[240:243], v[16:19]
	v_mfma_f32_16x16x32_bf16 v[8:11], v[192:195], v[240:243], v[8:11]
	v_mfma_f32_16x16x32_bf16 v[64:67], v[188:191], v[220:223], v[64:67]
	v_mfma_f32_16x16x32_bf16 v[56:59], v[196:199], v[220:223], v[56:59]
	v_mfma_f32_16x16x32_bf16 v[48:51], v[188:191], v[228:231], v[48:51]
	v_mfma_f32_16x16x32_bf16 v[40:43], v[196:199], v[228:231], v[40:43]
	v_mfma_f32_16x16x32_bf16 v[32:35], v[188:191], v[236:239], v[32:35]
	v_mfma_f32_16x16x32_bf16 v[24:27], v[196:199], v[236:239], v[24:27]
	v_mfma_f32_16x16x32_bf16 v[16:19], v[188:191], v[244:247], v[16:19]
	v_mfma_f32_16x16x32_bf16 v[8:11], v[196:199], v[244:247], v[8:11]
	s_setprio 0
	s_setprio 1
	v_mfma_f32_16x16x32_bf16 v[60:63], v[200:203], v[216:219], v[60:63]
	v_mfma_f32_16x16x32_bf16 v[52:55], v[208:211], v[216:219], v[52:55]
	v_mfma_f32_16x16x32_bf16 v[44:47], v[200:203], v[224:227], v[44:47]
	v_mfma_f32_16x16x32_bf16 v[36:39], v[208:211], v[224:227], v[36:39]
	v_mfma_f32_16x16x32_bf16 v[28:31], v[200:203], v[232:235], v[28:31]
	v_mfma_f32_16x16x32_bf16 v[20:23], v[208:211], v[232:235], v[20:23]
	v_mfma_f32_16x16x32_bf16 v[12:15], v[200:203], v[240:243], v[12:15]
	v_mfma_f32_16x16x32_bf16 v[4:7], v[208:211], v[240:243], v[4:7]
	v_mfma_f32_16x16x32_bf16 v[60:63], v[204:207], v[220:223], v[60:63]
	v_mfma_f32_16x16x32_bf16 v[52:55], v[212:215], v[220:223], v[52:55]
	v_mfma_f32_16x16x32_bf16 v[44:47], v[204:207], v[228:231], v[44:47]
	v_mfma_f32_16x16x32_bf16 v[36:39], v[212:215], v[228:231], v[36:39]
	v_mfma_f32_16x16x32_bf16 v[28:31], v[204:207], v[236:239], v[28:31]
	v_mfma_f32_16x16x32_bf16 v[20:23], v[212:215], v[236:239], v[20:23]
	v_mfma_f32_16x16x32_bf16 v[12:15], v[204:207], v[244:247], v[12:15]
	v_mfma_f32_16x16x32_bf16 v[4:7], v[212:215], v[244:247], v[4:7]
	s_setprio 0
	s_barrier
	s_add_i32 s51, s51, 2
	s_add_u32 s18, s18, 0x100
	s_addc_u32 s19, s19, 0
	s_add_u32 s45, s45, 0x100
	s_addc_u32 s50, s50, 0
	s_cmp_gt_u32 s51, 29
	s_cbranch_scc0 .LBB0_85
	s_and_b64 vcc, exec, s[6:7]
	s_cbranch_vccz .LBB0_88
	s_barrier

; #define PG8_STAGE(bufoff, gbase, voff) do { _Pragma("unroll") for (int _i = 0; _i < 2; ++_i) \
;         __builtin_amdgcn_global_load_lds((const unsigned*)((const char*)(gbase) + (voff)[_i]), (PG8_LAS unsigned*)(lds + (bufoff) + ldsw + _i * 8192), 16, 0, 0); } while (0)
; #define PG8_LDA(dst, b, h) do { _Pragma("unroll") for (int m = 0; m < 4; ++m) _Pragma("unroll") for (int k = 0; k < 2; ++k) dst[m][k] = *(const PG8_LAS bf16x8*)(lds + PG8_SA(b, h) + aoff + m * 2048 + k * 1024); } while (0)
; #define PG8_LDB(dst, b, h) do { _Pragma("unroll") for (int n = 0; n < 2; ++n) _Pragma("unroll") for (int k = 0; k < 2; ++k) dst[n][k] = *(const PG8_LAS bf16x8*)(lds + PG8_SB(b, h) + boff + n * 2048 + k * 1024); } while (0)
; #define PG8_MMA(ai, bj, At, Bt) do { __builtin_amdgcn_s_setprio(1); _Pragma("unroll") for (int m = 0; m < 4; ++m) _Pragma("unroll") for (int n = 0; n < 2; ++n) _Pragma("unroll") for (int k = 0; k < 2; ++k) \
;         acc[ai][bj][m][n] = __builtin_amdgcn_mfma_f32_16x16x32_bf16(Bt[n][k], At[m][k], acc[ai][bj][m][n], 0, 0, 0); __builtin_amdgcn_s_setprio(0); } while (0)
; #define PG8_WAIT_V(n) asm volatile("s_waitcnt vmcnt(" #n ")" ::: "memory")
; #define PG8_WAIT_L(n) asm volatile("s_waitcnt lgkmcnt(" #n ")" ::: "memory")
; template <class Epi, class Sched, bool ALIGN_EPI = false, bool SP2 = false>
; __device__ __forceinline__ void gemm_phase(PG8_LAS unsigned char* lds, const Gemm g, const Sched& S, const Epi& E) {
;     ...
;             const bool last = (t == nt - 2);
;             const char* a1 = cA + (size_t)(t + 1) * kstep;
;             const char* a2 = last ? nA : cA + (size_t)(t + 2) * kstep; const char* b2 = last ? nB : cB + (size_t)(t + 2) * kstep;
;             const char* a3 = a2 + kstep; const char* b3 = b2 + kstep;
;             if (last && has_next) S.a_ready(nxt);
;             if constexpr (SP2) {
;             PG8_LDB(B0, 0, 0); PG8_LDB(B1, 0, 1); PG8_SCHED; PG8_LDA(At, 0, 0); PG8_STAGE(PG8_SA(1, 1), a1 + hstep, voffA);
;             PG8_WAIT_V(8); PG8_WAIT_L(0); PG8_BAR; PG8_MMA(0, 0, At, B0); PG8_MMA(0, 1, At, B1); PG8_BAR; PG8_SCHED;
;             PG8_LDA(At, 0, 1); PG8_STAGE(PG8_SB(0, 0), b2, voffB); PG8_STAGE(PG8_SB(0, 1), b2 + hstep, voffB); PG8_STAGE(PG8_SA(0, 0), a2, voffA);
;             PG8_WAIT_V(8); PG8_WAIT_L(0); PG8_BAR; PG8_MMA(1, 0, At, B0); PG8_MMA(1, 1, At, B1); PG8_BAR; PG8_SCHED;
.LBB0_167:
	s_add_u32 s16, s14, 0x100
	s_addc_u32 s17, s15, 0
	s_add_i32 s63, 0, 0x10000
	s_cmpk_eq_i32 s57, 0x54
	s_cselect_b32 s21, s7, s17
	s_cselect_b32 s20, s6, s16
	s_cselect_b32 s19, s13, s56
	s_cselect_b32 s18, s12, s51
	s_add_i32 s64, 0, 0x14000
	v_add_u32_e32 v162, s63, v185
	v_add_u32_e32 v166, s64, v185
	ds_read_b128 v[132:135], v162
	ds_read_b128 v[136:139], v162 offset:1024
	ds_read_b128 v[158:161], v162 offset:2048
	ds_read_b128 v[162:165], v162 offset:3072
	ds_read_b128 v[188:191], v166
	ds_read_b128 v[192:195], v166 offset:1024
	ds_read_b128 v[196:199], v166 offset:2048
	ds_read_b128 v[200:203], v166 offset:3072
	s_add_i32 m0, s26, 0xc000
	ds_read_b128 v[204:207], v187
	ds_read_b128 v[208:211], v187 offset:1024
	ds_read_b128 v[212:215], v187 offset:2048
	ds_read_b128 v[216:219], v187 offset:3072
	ds_read_b128 v[220:223], v187 offset:4096
	ds_read_b128 v[224:227], v187 offset:5120
	ds_read_b128 v[228:231], v187 offset:6144
	ds_read_b128 v[232:235], v187 offset:7168
	global_load_lds_dwordx4 v154, s[14:15]
	s_add_i32 m0, s26, 0xe000
	s_nop 0
	global_load_lds_dwordx4 v156, s[14:15]
	s_waitcnt vmcnt(8)
	s_waitcnt lgkmcnt(0)
	s_barrier
	s_setprio 1
	s_waitcnt lgkmcnt(0)
	v_mfma_f32_16x16x32_bf16 v[128:131], v[132:135], v[204:207], v[128:131]
	v_mfma_f32_16x16x32_bf16 v[124:127], v[158:161], v[204:207], v[124:127]
	v_mfma_f32_16x16x32_bf16 v[112:115], v[132:135], v[212:215], v[112:115]
	v_mfma_f32_16x16x32_bf16 v[108:111], v[158:161], v[212:215], v[108:111]
	v_mfma_f32_16x16x32_bf16 v[96:99], v[132:135], v[220:223], v[96:99]
	v_mfma_f32_16x16x32_bf16 v[92:95], v[158:161], v[220:223], v[92:95]
	v_mfma_f32_16x16x32_bf16 v[80:83], v[132:135], v[228:231], v[80:83]
	v_mfma_f32_16x16x32_bf16 v[76:79], v[158:161], v[228:231], v[76:79]
	v_mfma_f32_16x16x32_bf16 v[128:131], v[136:139], v[208:211], v[128:131]
	v_mfma_f32_16x16x32_bf16 v[124:127], v[162:165], v[208:211], v[124:127]
	v_mfma_f32_16x16x32_bf16 v[112:115], v[136:139], v[216:219], v[112:115]
	v_mfma_f32_16x16x32_bf16 v[108:111], v[162:165], v[216:219], v[108:111]
	v_mfma_f32_16x16x32_bf16 v[96:99], v[136:139], v[224:227], v[96:99]
	v_mfma_f32_16x16x32_bf16 v[92:95], v[162:165], v[224:227], v[92:95]
	v_mfma_f32_16x16x32_bf16 v[80:83], v[136:139], v[232:235], v[80:83]
	v_mfma_f32_16x16x32_bf16 v[76:79], v[162:165], v[232:235], v[76:79]
	s_setprio 0
	s_setprio 1
	v_mfma_f32_16x16x32_bf16 v[120:123], v[188:191], v[204:207], v[120:123]
	v_mfma_f32_16x16x32_bf16 v[116:119], v[196:199], v[204:207], v[116:119]
	v_mfma_f32_16x16x32_bf16 v[104:107], v[188:191], v[212:215], v[104:107]
	v_mfma_f32_16x16x32_bf16 v[100:103], v[196:199], v[212:215], v[100:103]
	v_mfma_f32_16x16x32_bf16 v[88:91], v[188:191], v[220:223], v[88:91]
	v_mfma_f32_16x16x32_bf16 v[84:87], v[196:199], v[220:223], v[84:87]
	v_mfma_f32_16x16x32_bf16 v[72:75], v[188:191], v[228:231], v[72:75]
	v_mfma_f32_16x16x32_bf16 v[68:71], v[196:199], v[228:231], v[68:71]
	v_mfma_f32_16x16x32_bf16 v[120:123], v[192:195], v[208:211], v[120:123]
	v_mfma_f32_16x16x32_bf16 v[116:119], v[200:203], v[208:211], v[116:119]
	v_mfma_f32_16x16x32_bf16 v[104:107], v[192:195], v[216:219], v[104:107]
	v_mfma_f32_16x16x32_bf16 v[100:103], v[200:203], v[216:219], v[100:103]
	v_mfma_f32_16x16x32_bf16 v[88:91], v[192:195], v[224:227], v[88:91]
	v_mfma_f32_16x16x32_bf16 v[84:87], v[200:203], v[224:227], v[84:87]
	v_mfma_f32_16x16x32_bf16 v[72:75], v[192:195], v[232:235], v[72:75]
	v_mfma_f32_16x16x32_bf16 v[68:71], v[200:203], v[232:235], v[68:71]
	s_setprio 0
	s_barrier
	s_add_i32 s14, s63, s25
	s_mov_b32 m0, s14
	ds_read_b128 v[204:207], v187 offset:16384
	ds_read_b128 v[208:211], v187 offset:17408
	ds_read_b128 v[212:215], v187 offset:18432
	ds_read_b128 v[216:219], v187 offset:19456
	ds_read_b128 v[220:223], v187 offset:20480
	ds_read_b128 v[224:227], v187 offset:21504
	ds_read_b128 v[228:231], v187 offset:22528
	ds_read_b128 v[232:235], v187 offset:23552
	global_load_lds_dwordx4 v2, s[18:19]
	s_add_i32 m0, s14, 0x2000
	s_add_u32 s14, s18, 0x160000
	v_lshl_add_u64 v[236:237], s[18:19], 0, v[152:153]
	s_addc_u32 s15, s19, 0
	s_add_i32 s63, s64, s25
	global_load_lds_dwordx4 v[236:237], off
	s_mov_b32 m0, s63
	global_load_lds_dwordx4 v2, s[14:15]
	s_add_i32 m0, s63, 0x2000
	s_nop 0
	global_load_lds_dwordx4 v152, s[14:15]
	s_mov_b32 m0, s26
	s_nop 0
	global_load_lds_dwordx4 v0, s[20:21]
	s_mov_b32 m0, s27
	s_nop 0
	global_load_lds_dwordx4 v150, s[20:21]
	s_waitcnt vmcnt(8)
	s_waitcnt lgkmcnt(0)
	s_barrier
	s_setprio 1
	s_waitcnt lgkmcnt(0)
	v_mfma_f32_16x16x32_bf16 v[64:67], v[132:135], v[204:207], v[64:67]
	v_mfma_f32_16x16x32_bf16 v[60:63], v[158:161], v[204:207], v[60:63]
	v_mfma_f32_16x16x32_bf16 v[48:51], v[132:135], v[212:215], v[48:51]
	v_mfma_f32_16x16x32_bf16 v[44:47], v[158:161], v[212:215], v[44:47]
	v_mfma_f32_16x16x32_bf16 v[32:35], v[132:135], v[220:223], v[32:35]
	v_mfma_f32_16x16x32_bf16 v[28:31], v[158:161], v[220:223], v[28:31]
	v_mfma_f32_16x16x32_bf16 v[16:19], v[132:135], v[228:231], v[16:19]
	v_mfma_f32_16x16x32_bf16 v[12:15], v[158:161], v[228:231], v[12:15]
	v_mfma_f32_16x16x32_bf16 v[64:67], v[136:139], v[208:211], v[64:67]
	v_mfma_f32_16x16x32_bf16 v[60:63], v[162:165], v[208:211], v[60:63]
	v_mfma_f32_16x16x32_bf16 v[48:51], v[136:139], v[216:219], v[48:51]
	v_mfma_f32_16x16x32_bf16 v[44:47], v[162:165], v[216:219], v[44:47]
	v_mfma_f32_16x16x32_bf16 v[32:35], v[136:139], v[224:227], v[32:35]
	v_mfma_f32_16x16x32_bf16 v[28:31], v[162:165], v[224:227], v[28:31]
	v_mfma_f32_16x16x32_bf16 v[16:19], v[136:139], v[232:235], v[16:19]
	v_mfma_f32_16x16x32_bf16 v[12:15], v[162:165], v[232:235], v[12:15]
	s_setprio 0
	s_setprio 1
	v_mfma_f32_16x16x32_bf16 v[56:59], v[188:191], v[204:207], v[56:59]
	v_mfma_f32_16x16x32_bf16 v[52:55], v[196:199], v[204:207], v[52:55]
	v_mfma_f32_16x16x32_bf16 v[40:43], v[188:191], v[212:215], v[40:43]
	v_mfma_f32_16x16x32_bf16 v[36:39], v[196:199], v[212:215], v[36:39]
	v_mfma_f32_16x16x32_bf16 v[24:27], v[188:191], v[220:223], v[24:27]
	v_mfma_f32_16x16x32_bf16 v[20:23], v[196:199], v[220:223], v[20:23]
	v_mfma_f32_16x16x32_bf16 v[8:11], v[188:191], v[228:231], v[8:11]
	v_mfma_f32_16x16x32_bf16 v[4:7], v[196:199], v[228:231], v[4:7]
	v_mfma_f32_16x16x32_bf16 v[56:59], v[192:195], v[208:211], v[56:59]
	v_mfma_f32_16x16x32_bf16 v[52:55], v[200:203], v[208:211], v[52:55]
	v_mfma_f32_16x16x32_bf16 v[40:43], v[192:195], v[216:219], v[40:43]
	v_mfma_f32_16x16x32_bf16 v[36:39], v[200:203], v[216:219], v[36:39]
	v_mfma_f32_16x16x32_bf16 v[24:27], v[192:195], v[224:227], v[24:27]
	v_mfma_f32_16x16x32_bf16 v[20:23], v[200:203], v[224:227], v[20:23]
	v_mfma_f32_16x16x32_bf16 v[8:11], v[192:195], v[232:235], v[8:11]
	v_mfma_f32_16x16x32_bf16 v[4:7], v[200:203], v[232:235], v[4:7]
	s_setprio 0
	s_barrier
; #define PG8_STAGE(bufoff, gbase, voff) do { _Pragma("unroll") for (int _i = 0; _i < 2; ++_i) \
;         __builtin_amdgcn_global_load_lds((const unsigned*)((const char*)(gbase) + (voff)[_i]), (PG8_LAS unsigned*)(lds + (bufoff) + ldsw + _i * 8192), 16, 0, 0); } while (0)
; #define PG8_LDA(dst, b, h) do { _Pragma("unroll") for (int m = 0; m < 4; ++m) _Pragma("unroll") for (int k = 0; k < 2; ++k) dst[m][k] = *(const PG8_LAS bf16x8*)(lds + PG8_SA(b, h) + aoff + m * 2048 + k * 1024); } while (0)
; #define PG8_LDB(dst, b, h) do { _Pragma("unroll") for (int n = 0; n < 2; ++n) _Pragma("unroll") for (int k = 0; k < 2; ++k) dst[n][k] = *(const PG8_LAS bf16x8*)(lds + PG8_SB(b, h) + boff + n * 2048 + k * 1024); } while (0)
; #define PG8_MMA(ai, bj, At, Bt) do { __builtin_amdgcn_s_setprio(1); _Pragma("unroll") for (int m = 0; m < 4; ++m) _Pragma("unroll") for (int n = 0; n < 2; ++n) _Pragma("unroll") for (int k = 0; k < 2; ++k) \
;         acc[ai][bj][m][n] = __builtin_amdgcn_mfma_f32_16x16x32_bf16(Bt[n][k], At[m][k], acc[ai][bj][m][n], 0, 0, 0); __builtin_amdgcn_s_setprio(0); } while (0)
; #define PG8_WAIT_V(n) asm volatile("s_waitcnt vmcnt(" #n ")" ::: "memory")
; #define PG8_WAIT_L(n) asm volatile("s_waitcnt lgkmcnt(" #n ")" ::: "memory")
; #define PG8_BAR __builtin_amdgcn_s_barrier()
; #define PG8_SCHED __builtin_amdgcn_sched_barrier(0)
; template <class Epi, class Sched, bool ALIGN_EPI = false, bool SP2 = false>
; __device__ __forceinline__ void gemm_phase(PG8_LAS unsigned char* lds, const Gemm g, const Sched& S, const Epi& E) {
;     ...
;             PG8_LDB(B0, 1, 0); PG8_LDB(B1, 1, 1); PG8_SCHED; PG8_LDA(At, 1, 0); PG8_STAGE(PG8_SA(0, 1), a2 + hstep, voffA);
;             PG8_WAIT_V(8); PG8_WAIT_L(0); PG8_BAR; PG8_MMA(0, 0, At, B0); PG8_MMA(0, 1, At, B1); PG8_BAR; PG8_SCHED;
;             PG8_LDA(At, 1, 1); PG8_STAGE(PG8_SB(1, 0), b3, voffB); PG8_STAGE(PG8_SB(1, 1), b3 + hstep, voffB); PG8_STAGE(PG8_SA(1, 0), a3, voffA);
;             PG8_WAIT_V(8); PG8_WAIT_L(0); PG8_BAR; PG8_MMA(1, 0, At, B0); PG8_MMA(1, 1, At, B1); PG8_BAR; PG8_SCHED;
	s_add_i32 s63, 0, 0x18000
	s_add_i32 s64, 0, 0x1c000
	v_add_u32_e32 v162, s63, v185
	v_add_u32_e32 v200, s64, v185
	ds_read_b128 v[132:135], v162
	ds_read_b128 v[136:139], v162 offset:1024
	ds_read_b128 v[158:161], v162 offset:2048
	ds_read_b128 v[162:165], v162 offset:3072
	ds_read_b128 v[188:191], v200
	ds_read_b128 v[192:195], v200 offset:1024
	ds_read_b128 v[196:199], v200 offset:2048
	ds_read_b128 v[200:203], v200 offset:3072
	s_add_u32 s14, s20, 0x160000
	s_addc_u32 s15, s21, 0
	s_mov_b32 m0, s28
	ds_read_b128 v[204:207], v187 offset:32768
	ds_read_b128 v[208:211], v187 offset:33792
	ds_read_b128 v[212:215], v187 offset:34816
	ds_read_b128 v[216:219], v187 offset:35840
	ds_read_b128 v[220:223], v187 offset:36864
	ds_read_b128 v[224:227], v187 offset:37888
	ds_read_b128 v[228:231], v187 offset:38912
	ds_read_b128 v[232:235], v187 offset:39936
	global_load_lds_dwordx4 v0, s[14:15]
	s_mov_b32 m0, s29
	s_nop 0
	global_load_lds_dwordx4 v150, s[14:15]
	s_waitcnt vmcnt(8)
	s_waitcnt lgkmcnt(0)
	s_barrier
	s_setprio 1
	s_waitcnt lgkmcnt(0)
	v_mfma_f32_16x16x32_bf16 v[128:131], v[132:135], v[204:207], v[128:131]
	v_mfma_f32_16x16x32_bf16 v[124:127], v[158:161], v[204:207], v[124:127]
	v_mfma_f32_16x16x32_bf16 v[112:115], v[132:135], v[212:215], v[112:115]
	v_mfma_f32_16x16x32_bf16 v[108:111], v[158:161], v[212:215], v[108:111]
	v_mfma_f32_16x16x32_bf16 v[96:99], v[132:135], v[220:223], v[96:99]
	v_mfma_f32_16x16x32_bf16 v[92:95], v[158:161], v[220:223], v[92:95]
	v_mfma_f32_16x16x32_bf16 v[80:83], v[132:135], v[228:231], v[80:83]
	v_mfma_f32_16x16x32_bf16 v[76:79], v[158:161], v[228:231], v[76:79]
	v_mfma_f32_16x16x32_bf16 v[128:131], v[136:139], v[208:211], v[128:131]
	v_mfma_f32_16x16x32_bf16 v[124:127], v[162:165], v[208:211], v[124:127]
	v_mfma_f32_16x16x32_bf16 v[112:115], v[136:139], v[216:219], v[112:115]
	v_mfma_f32_16x16x32_bf16 v[108:111], v[162:165], v[216:219], v[108:111]
	v_mfma_f32_16x16x32_bf16 v[96:99], v[136:139], v[224:227], v[96:99]
	v_mfma_f32_16x16x32_bf16 v[92:95], v[162:165], v[224:227], v[92:95]
	v_mfma_f32_16x16x32_bf16 v[80:83], v[136:139], v[232:235], v[80:83]
	v_mfma_f32_16x16x32_bf16 v[76:79], v[162:165], v[232:235], v[76:79]
	s_setprio 0
	s_setprio 1
	v_mfma_f32_16x16x32_bf16 v[120:123], v[188:191], v[204:207], v[120:123]
	v_mfma_f32_16x16x32_bf16 v[116:119], v[196:199], v[204:207], v[116:119]
	v_mfma_f32_16x16x32_bf16 v[104:107], v[188:191], v[212:215], v[104:107]
	v_mfma_f32_16x16x32_bf16 v[100:103], v[196:199], v[212:215], v[100:103]
	v_mfma_f32_16x16x32_bf16 v[88:91], v[188:191], v[220:223], v[88:91]
	v_mfma_f32_16x16x32_bf16 v[84:87], v[196:199], v[220:223], v[84:87]
	v_mfma_f32_16x16x32_bf16 v[72:75], v[188:191], v[228:231], v[72:75]
	v_mfma_f32_16x16x32_bf16 v[68:71], v[196:199], v[228:231], v[68:71]
	v_mfma_f32_16x16x32_bf16 v[120:123], v[192:195], v[208:211], v[120:123]
	v_mfma_f32_16x16x32_bf16 v[116:119], v[200:203], v[208:211], v[116:119]
	v_mfma_f32_16x16x32_bf16 v[104:107], v[192:195], v[216:219], v[104:107]
	v_mfma_f32_16x16x32_bf16 v[100:103], v[200:203], v[216:219], v[100:103]
	v_mfma_f32_16x16x32_bf16 v[88:91], v[192:195], v[224:227], v[88:91]
	v_mfma_f32_16x16x32_bf16 v[84:87], v[200:203], v[224:227], v[84:87]
	v_mfma_f32_16x16x32_bf16 v[72:75], v[192:195], v[232:235], v[72:75]
	v_mfma_f32_16x16x32_bf16 v[68:71], v[200:203], v[232:235], v[68:71]
	s_setprio 0
	s_barrier
	s_add_i32 s14, s63, s25
	s_mov_b32 m0, s14
	ds_read_b128 v[204:207], v187 offset:49152
	ds_read_b128 v[208:211], v187 offset:50176
	ds_read_b128 v[212:215], v187 offset:51200
	ds_read_b128 v[216:219], v187 offset:52224
	ds_read_b128 v[220:223], v187 offset:53248
	ds_read_b128 v[224:227], v187 offset:54272
	ds_read_b128 v[228:231], v187 offset:55296
	ds_read_b128 v[232:235], v187 offset:56320
	s_add_u32 vcc_lo, s18, 0x80
	s_addc_u32 vcc_hi, s19, 0
	global_load_lds_dwordx4 v2, vcc
	s_add_i32 m0, s14, 0x2000
	s_add_u32 s14, s18, 0x160080
	v_lshl_add_u64 v[166:167], v[236:237], 0, s[36:37]
	s_addc_u32 s15, s19, 0
	s_add_i32 s18, s64, s25
	global_load_lds_dwordx4 v[166:167], off
	s_mov_b32 m0, s18
	s_nop 0
	global_load_lds_dwordx4 v2, s[14:15]
	v_lshl_add_u64 v[166:167], s[14:15], 0, v[152:153]
	s_add_i32 m0, s18, 0x2000
	s_nop 0
	global_load_lds_dwordx4 v[166:167], off
	s_mov_b32 m0, s30
	s_nop 0
	s_add_u32 vcc_lo, s20, 0x80
	s_addc_u32 vcc_hi, s21, 0
	global_load_lds_dwordx4 v0, vcc
	s_mov_b32 m0, s31
	s_nop 0
	s_add_u32 vcc_lo, s20, 0x80
	s_addc_u32 vcc_hi, s21, 0
	global_load_lds_dwordx4 v150, vcc
	s_waitcnt vmcnt(8)
	s_waitcnt lgkmcnt(0)
	s_barrier
	s_setprio 1
	s_waitcnt lgkmcnt(0)
	v_mfma_f32_16x16x32_bf16 v[64:67], v[132:135], v[204:207], v[64:67]
	v_mfma_f32_16x16x32_bf16 v[60:63], v[158:161], v[204:207], v[60:63]
	v_mfma_f32_16x16x32_bf16 v[48:51], v[132:135], v[212:215], v[48:51]
	v_mfma_f32_16x16x32_bf16 v[44:47], v[158:161], v[212:215], v[44:47]
	v_mfma_f32_16x16x32_bf16 v[32:35], v[132:135], v[220:223], v[32:35]
	v_mfma_f32_16x16x32_bf16 v[28:31], v[158:161], v[220:223], v[28:31]
	v_mfma_f32_16x16x32_bf16 v[16:19], v[132:135], v[228:231], v[16:19]
	v_mfma_f32_16x16x32_bf16 v[12:15], v[158:161], v[228:231], v[12:15]
	v_mfma_f32_16x16x32_bf16 v[64:67], v[136:139], v[208:211], v[64:67]
	v_mfma_f32_16x16x32_bf16 v[60:63], v[162:165], v[208:211], v[60:63]
	v_mfma_f32_16x16x32_bf16 v[48:51], v[136:139], v[216:219], v[48:51]
	v_mfma_f32_16x16x32_bf16 v[44:47], v[162:165], v[216:219], v[44:47]
	v_mfma_f32_16x16x32_bf16 v[32:35], v[136:139], v[224:227], v[32:35]
	v_mfma_f32_16x16x32_bf16 v[28:31], v[162:165], v[224:227], v[28:31]
	v_mfma_f32_16x16x32_bf16 v[16:19], v[136:139], v[232:235], v[16:19]
	v_mfma_f32_16x16x32_bf16 v[12:15], v[162:165], v[232:235], v[12:15]
	s_setprio 0
	s_setprio 1
	v_mfma_f32_16x16x32_bf16 v[56:59], v[188:191], v[204:207], v[56:59]
	v_mfma_f32_16x16x32_bf16 v[52:55], v[196:199], v[204:207], v[52:55]
	v_mfma_f32_16x16x32_bf16 v[40:43], v[188:191], v[212:215], v[40:43]
	v_mfma_f32_16x16x32_bf16 v[36:39], v[196:199], v[212:215], v[36:39]
	v_mfma_f32_16x16x32_bf16 v[24:27], v[188:191], v[220:223], v[24:27]
	v_mfma_f32_16x16x32_bf16 v[20:23], v[196:199], v[220:223], v[20:23]
	v_mfma_f32_16x16x32_bf16 v[8:11], v[188:191], v[228:231], v[8:11]
	v_mfma_f32_16x16x32_bf16 v[4:7], v[196:199], v[228:231], v[4:7]
	v_mfma_f32_16x16x32_bf16 v[56:59], v[192:195], v[208:211], v[56:59]
	v_mfma_f32_16x16x32_bf16 v[52:55], v[200:203], v[208:211], v[52:55]
	v_mfma_f32_16x16x32_bf16 v[40:43], v[192:195], v[216:219], v[40:43]
	v_mfma_f32_16x16x32_bf16 v[36:39], v[200:203], v[216:219], v[36:39]
	v_mfma_f32_16x16x32_bf16 v[24:27], v[192:195], v[224:227], v[24:27]
	v_mfma_f32_16x16x32_bf16 v[20:23], v[200:203], v[224:227], v[20:23]
	v_mfma_f32_16x16x32_bf16 v[8:11], v[192:195], v[232:235], v[8:11]
	v_mfma_f32_16x16x32_bf16 v[4:7], v[200:203], v[232:235], v[4:7]
	s_setprio 0
	s_barrier
	s_add_i32 s57, s57, 2
	s_add_u32 s51, s51, 0x100
	s_addc_u32 s56, s56, 0
	s_cmpk_gt_u32 s57, 0x55
	s_mov_b64 s[14:15], s[16:17]
	s_cbranch_scc0 .LBB0_167
	s_and_b64 vcc, exec, s[10:11]
	s_cbranch_vccz .LBB0_170
	s_barrier

; #define PG8_STAGE(bufoff, gbase, voff) do { _Pragma("unroll") for (int _i = 0; _i < 2; ++_i) \
;         __builtin_amdgcn_global_load_lds((const unsigned*)((const char*)(gbase) + (voff)[_i]), (PG8_LAS unsigned*)(lds + (bufoff) + ldsw + _i * 8192), 16, 0, 0); } while (0)
; #define PG8_LDA(dst, b, h) do { _Pragma("unroll") for (int m = 0; m < 4; ++m) _Pragma("unroll") for (int k = 0; k < 2; ++k) dst[m][k] = *(const PG8_LAS bf16x8*)(lds + PG8_SA(b, h) + aoff + m * 2048 + k * 1024); } while (0)
; #define PG8_LDB(dst, b, h) do { _Pragma("unroll") for (int n = 0; n < 2; ++n) _Pragma("unroll") for (int k = 0; k < 2; ++k) dst[n][k] = *(const PG8_LAS bf16x8*)(lds + PG8_SB(b, h) + boff + n * 2048 + k * 1024); } while (0)
; #define PG8_MMA(ai, bj, At, Bt) do { __builtin_amdgcn_s_setprio(1); _Pragma("unroll") for (int m = 0; m < 4; ++m) _Pragma("unroll") for (int n = 0; n < 2; ++n) _Pragma("unroll") for (int k = 0; k < 2; ++k) \
;         acc[ai][bj][m][n] = __builtin_amdgcn_mfma_f32_16x16x32_bf16(Bt[n][k], At[m][k], acc[ai][bj][m][n], 0, 0, 0); __builtin_amdgcn_s_setprio(0); } while (0)
; #define PG8_WAIT_V(n) asm volatile("s_waitcnt vmcnt(" #n ")" ::: "memory")
; #define PG8_WAIT_L(n) asm volatile("s_waitcnt lgkmcnt(" #n ")" ::: "memory")
; template <class Epi, class Sched, bool ALIGN_EPI = false, bool SP2 = false>
; __device__ __forceinline__ void gemm_phase(PG8_LAS unsigned char* lds, const Gemm g, const Sched& S, const Epi& E) {
;     ...
;             const bool last = (t == nt - 2);
;             const char* a1 = cA + (size_t)(t + 1) * kstep;
;             const char* a2 = last ? nA : cA + (size_t)(t + 2) * kstep; const char* b2 = last ? nB : cB + (size_t)(t + 2) * kstep;
;             const char* a3 = a2 + kstep; const char* b3 = b2 + kstep;
;             if (last && has_next) S.a_ready(nxt);
;             if constexpr (SP2) {
;             PG8_LDB(B0, 0, 0); PG8_LDB(B1, 0, 1); PG8_SCHED; PG8_LDA(At, 0, 0); PG8_STAGE(PG8_SA(1, 1), a1 + hstep, voffA);
;             PG8_WAIT_V(8); PG8_WAIT_L(0); PG8_BAR; PG8_MMA(0, 0, At, B0); PG8_MMA(0, 1, At, B1); PG8_BAR; PG8_SCHED;
;             PG8_LDA(At, 0, 1); PG8_STAGE(PG8_SB(0, 0), b2, voffB); PG8_STAGE(PG8_SB(0, 1), b2 + hstep, voffB); PG8_STAGE(PG8_SA(0, 0), a2, voffA);
;             PG8_WAIT_V(8); PG8_WAIT_L(0); PG8_BAR; PG8_MMA(1, 0, At, B0); PG8_MMA(1, 1, At, B1); PG8_BAR; PG8_SCHED;
.LBB0_251:
	s_add_u32 s20, s18, 0xfff80080
	s_addc_u32 s21, s19, -1
	s_add_i32 s63, 0, 0x10000
	s_cmp_eq_u32 s57, 28
	s_cselect_b32 s23, s11, s21
	s_cselect_b32 s22, s45, s20
	v_add_u32_e32 v151, s63, v156
	s_cselect_b32 s21, s7, s56
	s_cselect_b32 s20, s50, s51
	s_add_i32 s66, 0, 0x14000
	ds_read_b128 v[184:187], v151
	ds_read_b128 v[188:191], v151 offset:1024
	ds_read_b128 v[192:195], v151 offset:2048
	ds_read_b128 v[196:199], v151 offset:3072
	v_add_u32_e32 v151, s66, v156
	ds_read_b128 v[200:203], v151
	ds_read_b128 v[204:207], v151 offset:1024
	ds_read_b128 v[208:211], v151 offset:2048
	ds_read_b128 v[212:215], v151 offset:3072
	s_add_i32 m0, s17, 0xc000
	ds_read_b128 v[216:219], v160
	ds_read_b128 v[220:223], v160 offset:1024
	ds_read_b128 v[224:227], v160 offset:2048
	ds_read_b128 v[228:231], v160 offset:3072
	ds_read_b128 v[232:235], v160 offset:4096
	ds_read_b128 v[236:239], v160 offset:5120
	ds_read_b128 v[240:243], v160 offset:6144
	ds_read_b128 v[244:247], v160 offset:7168
	global_load_lds_dwordx4 v136, s[18:19]
	s_add_i32 m0, s17, 0xe000
	s_nop 0
	global_load_lds_dwordx4 v138, s[18:19]
	s_waitcnt vmcnt(8)
	s_waitcnt lgkmcnt(0)
	s_barrier
	s_setprio 1
	s_waitcnt lgkmcnt(0)
	v_mfma_f32_16x16x32_bf16 v[128:131], v[184:187], v[216:219], v[128:131]
	v_mfma_f32_16x16x32_bf16 v[124:127], v[192:195], v[216:219], v[124:127]
	v_mfma_f32_16x16x32_bf16 v[112:115], v[184:187], v[224:227], v[112:115]
	v_mfma_f32_16x16x32_bf16 v[108:111], v[192:195], v[224:227], v[108:111]
	v_mfma_f32_16x16x32_bf16 v[96:99], v[184:187], v[232:235], v[96:99]
	v_mfma_f32_16x16x32_bf16 v[92:95], v[192:195], v[232:235], v[92:95]
	v_mfma_f32_16x16x32_bf16 v[80:83], v[184:187], v[240:243], v[80:83]
	v_mfma_f32_16x16x32_bf16 v[76:79], v[192:195], v[240:243], v[76:79]
	v_mfma_f32_16x16x32_bf16 v[128:131], v[188:191], v[220:223], v[128:131]
	v_mfma_f32_16x16x32_bf16 v[124:127], v[196:199], v[220:223], v[124:127]
	v_mfma_f32_16x16x32_bf16 v[112:115], v[188:191], v[228:231], v[112:115]
	v_mfma_f32_16x16x32_bf16 v[108:111], v[196:199], v[228:231], v[108:111]
	v_mfma_f32_16x16x32_bf16 v[96:99], v[188:191], v[236:239], v[96:99]
	v_mfma_f32_16x16x32_bf16 v[92:95], v[196:199], v[236:239], v[92:95]
	v_mfma_f32_16x16x32_bf16 v[80:83], v[188:191], v[244:247], v[80:83]
	v_mfma_f32_16x16x32_bf16 v[76:79], v[196:199], v[244:247], v[76:79]
	s_setprio 0
	s_setprio 1
	v_mfma_f32_16x16x32_bf16 v[120:123], v[200:203], v[216:219], v[120:123]
	v_mfma_f32_16x16x32_bf16 v[116:119], v[208:211], v[216:219], v[116:119]
	v_mfma_f32_16x16x32_bf16 v[104:107], v[200:203], v[224:227], v[104:107]
	v_mfma_f32_16x16x32_bf16 v[100:103], v[208:211], v[224:227], v[100:103]
	v_mfma_f32_16x16x32_bf16 v[88:91], v[200:203], v[232:235], v[88:91]
	v_mfma_f32_16x16x32_bf16 v[84:87], v[208:211], v[232:235], v[84:87]
	v_mfma_f32_16x16x32_bf16 v[72:75], v[200:203], v[240:243], v[72:75]
	v_mfma_f32_16x16x32_bf16 v[68:71], v[208:211], v[240:243], v[68:71]
	v_mfma_f32_16x16x32_bf16 v[120:123], v[204:207], v[220:223], v[120:123]
	v_mfma_f32_16x16x32_bf16 v[116:119], v[212:215], v[220:223], v[116:119]
	v_mfma_f32_16x16x32_bf16 v[104:107], v[204:207], v[228:231], v[104:107]
	v_mfma_f32_16x16x32_bf16 v[100:103], v[212:215], v[228:231], v[100:103]
	v_mfma_f32_16x16x32_bf16 v[88:91], v[204:207], v[236:239], v[88:91]
	v_mfma_f32_16x16x32_bf16 v[84:87], v[212:215], v[236:239], v[84:87]
	v_mfma_f32_16x16x32_bf16 v[72:75], v[204:207], v[244:247], v[72:75]
	v_mfma_f32_16x16x32_bf16 v[68:71], v[212:215], v[244:247], v[68:71]
	s_setprio 0
	s_barrier
	s_add_i32 s63, s63, s27
	s_mov_b32 m0, s63
	ds_read_b128 v[216:219], v160 offset:16384
	ds_read_b128 v[220:223], v160 offset:17408
	ds_read_b128 v[224:227], v160 offset:18432
	ds_read_b128 v[228:231], v160 offset:19456
	ds_read_b128 v[232:235], v160 offset:20480
	ds_read_b128 v[236:239], v160 offset:21504
	ds_read_b128 v[240:243], v160 offset:22528
	ds_read_b128 v[244:247], v160 offset:23552
	global_load_lds_dwordx4 v2, s[20:21]
	s_add_i32 m0, s63, 0x2000
	s_add_u32 s64, s20, 0x80000
	s_addc_u32 s65, s21, 0
	s_add_i32 s63, s66, s27
	global_load_lds_dwordx4 v0, s[20:21]
	s_mov_b32 m0, s63
	v_lshl_add_u64 v[250:251], s[22:23], 0, v[132:133]
	global_load_lds_dwordx4 v2, s[64:65]
	s_add_i32 m0, s63, 0x2000
	s_nop 0
	global_load_lds_dwordx4 v0, s[64:65]
	v_lshl_add_u64 v[248:249], s[22:23], 0, v[134:135]
	s_mov_b32 m0, s17
	s_nop 0
	global_load_lds_dwordx4 v[248:249], off
	s_mov_b32 m0, s29
	s_nop 0
	global_load_lds_dwordx4 v[250:251], off
	s_waitcnt vmcnt(8)
	s_waitcnt lgkmcnt(0)
	s_barrier
; #define PG8_STAGE(bufoff, gbase, voff) do { _Pragma("unroll") for (int _i = 0; _i < 2; ++_i) \
;         __builtin_amdgcn_global_load_lds((const unsigned*)((const char*)(gbase) + (voff)[_i]), (PG8_LAS unsigned*)(lds + (bufoff) + ldsw + _i * 8192), 16, 0, 0); } while (0)
; #define PG8_LDA(dst, b, h) do { _Pragma("unroll") for (int m = 0; m < 4; ++m) _Pragma("unroll") for (int k = 0; k < 2; ++k) dst[m][k] = *(const PG8_LAS bf16x8*)(lds + PG8_SA(b, h) + aoff + m * 2048 + k * 1024); } while (0)
; #define PG8_LDB(dst, b, h) do { _Pragma("unroll") for (int n = 0; n < 2; ++n) _Pragma("unroll") for (int k = 0; k < 2; ++k) dst[n][k] = *(const PG8_LAS bf16x8*)(lds + PG8_SB(b, h) + boff + n * 2048 + k * 1024); } while (0)
; #define PG8_MMA(ai, bj, At, Bt) do { __builtin_amdgcn_s_setprio(1); _Pragma("unroll") for (int m = 0; m < 4; ++m) _Pragma("unroll") for (int n = 0; n < 2; ++n) _Pragma("unroll") for (int k = 0; k < 2; ++k) \
;         acc[ai][bj][m][n] = __builtin_amdgcn_mfma_f32_16x16x32_bf16(Bt[n][k], At[m][k], acc[ai][bj][m][n], 0, 0, 0); __builtin_amdgcn_s_setprio(0); } while (0)
; #define PG8_WAIT_V(n) asm volatile("s_waitcnt vmcnt(" #n ")" ::: "memory")
; #define PG8_WAIT_L(n) asm volatile("s_waitcnt lgkmcnt(" #n ")" ::: "memory")
; #define PG8_BAR __builtin_amdgcn_s_barrier()
; #define PG8_SCHED __builtin_amdgcn_sched_barrier(0)
; template <class Epi, class Sched, bool ALIGN_EPI = false, bool SP2 = false>
; __device__ __forceinline__ void gemm_phase(PG8_LAS unsigned char* lds, const Gemm g, const Sched& S, const Epi& E) {
;     ...
;             PG8_WAIT_V(8); PG8_WAIT_L(0); PG8_BAR; PG8_MMA(1, 0, At, B0); PG8_MMA(1, 1, At, B1); PG8_BAR; PG8_SCHED;
;             PG8_LDB(B0, 1, 0); PG8_LDB(B1, 1, 1); PG8_SCHED; PG8_LDA(At, 1, 0); PG8_STAGE(PG8_SA(0, 1), a2 + hstep, voffA);
;             PG8_WAIT_V(8); PG8_WAIT_L(0); PG8_BAR; PG8_MMA(0, 0, At, B0); PG8_MMA(0, 1, At, B1); PG8_BAR; PG8_SCHED;
	s_setprio 1
	s_waitcnt lgkmcnt(0)
	v_mfma_f32_16x16x32_bf16 v[64:67], v[184:187], v[216:219], v[64:67]
	v_mfma_f32_16x16x32_bf16 v[60:63], v[192:195], v[216:219], v[60:63]
	v_mfma_f32_16x16x32_bf16 v[48:51], v[184:187], v[224:227], v[48:51]
	v_mfma_f32_16x16x32_bf16 v[44:47], v[192:195], v[224:227], v[44:47]
	v_mfma_f32_16x16x32_bf16 v[32:35], v[184:187], v[232:235], v[32:35]
	v_mfma_f32_16x16x32_bf16 v[28:31], v[192:195], v[232:235], v[28:31]
	v_mfma_f32_16x16x32_bf16 v[16:19], v[184:187], v[240:243], v[16:19]
	v_mfma_f32_16x16x32_bf16 v[12:15], v[192:195], v[240:243], v[12:15]
	v_mfma_f32_16x16x32_bf16 v[64:67], v[188:191], v[220:223], v[64:67]
	v_mfma_f32_16x16x32_bf16 v[60:63], v[196:199], v[220:223], v[60:63]
	v_mfma_f32_16x16x32_bf16 v[48:51], v[188:191], v[228:231], v[48:51]
	v_mfma_f32_16x16x32_bf16 v[44:47], v[196:199], v[228:231], v[44:47]
	v_mfma_f32_16x16x32_bf16 v[32:35], v[188:191], v[236:239], v[32:35]
	v_mfma_f32_16x16x32_bf16 v[28:31], v[196:199], v[236:239], v[28:31]
	v_mfma_f32_16x16x32_bf16 v[16:19], v[188:191], v[244:247], v[16:19]
	v_mfma_f32_16x16x32_bf16 v[12:15], v[196:199], v[244:247], v[12:15]
	s_setprio 0
	s_setprio 1
	v_mfma_f32_16x16x32_bf16 v[56:59], v[200:203], v[216:219], v[56:59]
	v_mfma_f32_16x16x32_bf16 v[52:55], v[208:211], v[216:219], v[52:55]
	v_mfma_f32_16x16x32_bf16 v[40:43], v[200:203], v[224:227], v[40:43]
	v_mfma_f32_16x16x32_bf16 v[36:39], v[208:211], v[224:227], v[36:39]
	v_mfma_f32_16x16x32_bf16 v[24:27], v[200:203], v[232:235], v[24:27]
	v_mfma_f32_16x16x32_bf16 v[20:23], v[208:211], v[232:235], v[20:23]
	v_mfma_f32_16x16x32_bf16 v[8:11], v[200:203], v[240:243], v[8:11]
	v_mfma_f32_16x16x32_bf16 v[4:7], v[208:211], v[240:243], v[4:7]
	v_mfma_f32_16x16x32_bf16 v[56:59], v[204:207], v[220:223], v[56:59]
	v_mfma_f32_16x16x32_bf16 v[52:55], v[212:215], v[220:223], v[52:55]
	v_mfma_f32_16x16x32_bf16 v[40:43], v[204:207], v[228:231], v[40:43]
	v_mfma_f32_16x16x32_bf16 v[36:39], v[212:215], v[228:231], v[36:39]
	v_mfma_f32_16x16x32_bf16 v[24:27], v[204:207], v[236:239], v[24:27]
	v_mfma_f32_16x16x32_bf16 v[20:23], v[212:215], v[236:239], v[20:23]
	v_mfma_f32_16x16x32_bf16 v[8:11], v[204:207], v[244:247], v[8:11]
	v_mfma_f32_16x16x32_bf16 v[4:7], v[212:215], v[244:247], v[4:7]
	s_setprio 0
	s_barrier
	s_add_i32 s63, 0, 0x18000
	v_add_u32_e32 v151, s63, v156
	s_add_i32 s64, 0, 0x1c000
	ds_read_b128 v[184:187], v151
	ds_read_b128 v[188:191], v151 offset:1024
	ds_read_b128 v[192:195], v151 offset:2048
	ds_read_b128 v[196:199], v151 offset:3072
	v_add_u32_e32 v151, s64, v156
	ds_read_b128 v[200:203], v151
	ds_read_b128 v[204:207], v151 offset:1024
	ds_read_b128 v[208:211], v151 offset:2048
	ds_read_b128 v[212:215], v151 offset:3072
	s_add_u32 s22, s22, 0x80000
	s_addc_u32 s23, s23, 0
	s_mov_b32 m0, s30
	ds_read_b128 v[216:219], v160 offset:32768
	ds_read_b128 v[220:223], v160 offset:33792
	ds_read_b128 v[224:227], v160 offset:34816
	ds_read_b128 v[228:231], v160 offset:35840
	ds_read_b128 v[232:235], v160 offset:36864
	ds_read_b128 v[236:239], v160 offset:37888
	ds_read_b128 v[240:243], v160 offset:38912
	ds_read_b128 v[244:247], v160 offset:39936
	global_load_lds_dwordx4 v134, s[22:23]
	s_mov_b32 m0, s31
	s_nop 0
	global_load_lds_dwordx4 v132, s[22:23]
	s_waitcnt vmcnt(8)
	s_waitcnt lgkmcnt(0)
	s_barrier
	s_setprio 1
	s_waitcnt lgkmcnt(0)
	v_mfma_f32_16x16x32_bf16 v[128:131], v[184:187], v[216:219], v[128:131]
	v_mfma_f32_16x16x32_bf16 v[124:127], v[192:195], v[216:219], v[124:127]
	v_mfma_f32_16x16x32_bf16 v[112:115], v[184:187], v[224:227], v[112:115]
	v_mfma_f32_16x16x32_bf16 v[108:111], v[192:195], v[224:227], v[108:111]
	v_mfma_f32_16x16x32_bf16 v[96:99], v[184:187], v[232:235], v[96:99]
	v_mfma_f32_16x16x32_bf16 v[92:95], v[192:195], v[232:235], v[92:95]
	v_mfma_f32_16x16x32_bf16 v[80:83], v[184:187], v[240:243], v[80:83]
	v_mfma_f32_16x16x32_bf16 v[76:79], v[192:195], v[240:243], v[76:79]
	v_mfma_f32_16x16x32_bf16 v[128:131], v[188:191], v[220:223], v[128:131]
	v_mfma_f32_16x16x32_bf16 v[124:127], v[196:199], v[220:223], v[124:127]
	v_mfma_f32_16x16x32_bf16 v[112:115], v[188:191], v[228:231], v[112:115]
	v_mfma_f32_16x16x32_bf16 v[108:111], v[196:199], v[228:231], v[108:111]
	v_mfma_f32_16x16x32_bf16 v[96:99], v[188:191], v[236:239], v[96:99]
	v_mfma_f32_16x16x32_bf16 v[92:95], v[196:199], v[236:239], v[92:95]
	v_mfma_f32_16x16x32_bf16 v[80:83], v[188:191], v[244:247], v[80:83]
	v_mfma_f32_16x16x32_bf16 v[76:79], v[196:199], v[244:247], v[76:79]
	s_setprio 0
	s_setprio 1
	v_mfma_f32_16x16x32_bf16 v[120:123], v[200:203], v[216:219], v[120:123]
	v_mfma_f32_16x16x32_bf16 v[116:119], v[208:211], v[216:219], v[116:119]
	v_mfma_f32_16x16x32_bf16 v[104:107], v[200:203], v[224:227], v[104:107]
	v_mfma_f32_16x16x32_bf16 v[100:103], v[208:211], v[224:227], v[100:103]
	v_mfma_f32_16x16x32_bf16 v[88:91], v[200:203], v[232:235], v[88:91]
	v_mfma_f32_16x16x32_bf16 v[84:87], v[208:211], v[232:235], v[84:87]
	v_mfma_f32_16x16x32_bf16 v[72:75], v[200:203], v[240:243], v[72:75]
	v_mfma_f32_16x16x32_bf16 v[68:71], v[208:211], v[240:243], v[68:71]
	v_mfma_f32_16x16x32_bf16 v[120:123], v[204:207], v[220:223], v[120:123]
	v_mfma_f32_16x16x32_bf16 v[116:119], v[212:215], v[220:223], v[116:119]
	v_mfma_f32_16x16x32_bf16 v[104:107], v[204:207], v[228:231], v[104:107]
	v_mfma_f32_16x16x32_bf16 v[100:103], v[212:215], v[228:231], v[100:103]
	v_mfma_f32_16x16x32_bf16 v[88:91], v[204:207], v[236:239], v[88:91]
	v_mfma_f32_16x16x32_bf16 v[84:87], v[212:215], v[236:239], v[84:87]
	v_mfma_f32_16x16x32_bf16 v[72:75], v[204:207], v[244:247], v[72:75]
	v_mfma_f32_16x16x32_bf16 v[68:71], v[212:215], v[244:247], v[68:71]
	s_setprio 0
	s_barrier
; #define PG8_STAGE(bufoff, gbase, voff) do { _Pragma("unroll") for (int _i = 0; _i < 2; ++_i) \
;         __builtin_amdgcn_global_load_lds((const unsigned*)((const char*)(gbase) + (voff)[_i]), (PG8_LAS unsigned*)(lds + (bufoff) + ldsw + _i * 8192), 16, 0, 0); } while (0)
; #define PG8_LDA(dst, b, h) do { _Pragma("unroll") for (int m = 0; m < 4; ++m) _Pragma("unroll") for (int k = 0; k < 2; ++k) dst[m][k] = *(const PG8_LAS bf16x8*)(lds + PG8_SA(b, h) + aoff + m * 2048 + k * 1024); } while (0)
; #define PG8_MMA(ai, bj, At, Bt) do { __builtin_amdgcn_s_setprio(1); _Pragma("unroll") for (int m = 0; m < 4; ++m) _Pragma("unroll") for (int n = 0; n < 2; ++n) _Pragma("unroll") for (int k = 0; k < 2; ++k) \
;         acc[ai][bj][m][n] = __builtin_amdgcn_mfma_f32_16x16x32_bf16(Bt[n][k], At[m][k], acc[ai][bj][m][n], 0, 0, 0); __builtin_amdgcn_s_setprio(0); } while (0)
; #define PG8_WAIT_V(n) asm volatile("s_waitcnt vmcnt(" #n ")" ::: "memory")
; #define PG8_WAIT_L(n) asm volatile("s_waitcnt lgkmcnt(" #n ")" ::: "memory")
; #define PG8_BAR __builtin_amdgcn_s_barrier()
; #define PG8_SCHED __builtin_amdgcn_sched_barrier(0)
; template <class Epi, class Sched, bool ALIGN_EPI = false, bool SP2 = false>
; __device__ __forceinline__ void gemm_phase(PG8_LAS unsigned char* lds, const Gemm g, const Sched& S, const Epi& E) {
;     ...
;             PG8_LDA(At, 1, 1); PG8_STAGE(PG8_SB(1, 0), b3, voffB); PG8_STAGE(PG8_SB(1, 1), b3 + hstep, voffB); PG8_STAGE(PG8_SA(1, 0), a3, voffA);
;             PG8_WAIT_V(8); PG8_WAIT_L(0); PG8_BAR; PG8_MMA(1, 0, At, B0); PG8_MMA(1, 1, At, B1); PG8_BAR; PG8_SCHED;
;     ...
;         if constexpr (ALIGN_EPI) { if (wr == 0) PG8_BAR; }
	s_add_i32 s22, s63, s27
	s_mov_b32 m0, s22
	ds_read_b128 v[216:219], v160 offset:49152
	ds_read_b128 v[220:223], v160 offset:50176
	ds_read_b128 v[224:227], v160 offset:51200
	ds_read_b128 v[228:231], v160 offset:52224
	ds_read_b128 v[232:235], v160 offset:53248
	ds_read_b128 v[236:239], v160 offset:54272
	ds_read_b128 v[240:243], v160 offset:55296
	ds_read_b128 v[244:247], v160 offset:56320
	s_add_u32 vcc_lo, s20, 0x80
	s_addc_u32 vcc_hi, s21, 0
	global_load_lds_dwordx4 v2, vcc
	s_add_i32 m0, s22, 0x2000
	s_add_u32 s20, s20, 0x80080
	s_addc_u32 s21, s21, 0
	s_add_i32 s22, s64, s27
	s_add_u32 vcc_lo, s20, 0xfff80000
	s_addc_u32 vcc_hi, s21, -1
	global_load_lds_dwordx4 v0, vcc
	s_mov_b32 m0, s22
	s_nop 0
	global_load_lds_dwordx4 v2, s[20:21]
	s_add_i32 m0, s22, 0x2000
	s_nop 0
	global_load_lds_dwordx4 v0, s[20:21]
	v_lshl_add_u64 v[152:153], v[248:249], 0, s[36:37]
	s_mov_b32 m0, s34
	s_nop 0
	global_load_lds_dwordx4 v[152:153], off
	v_lshl_add_u64 v[152:153], v[250:251], 0, s[36:37]
	s_mov_b32 m0, s35
	s_nop 0
	global_load_lds_dwordx4 v[152:153], off
	s_waitcnt vmcnt(8)
	s_waitcnt lgkmcnt(0)
	s_barrier
	s_setprio 1
	s_waitcnt lgkmcnt(0)
	v_mfma_f32_16x16x32_bf16 v[64:67], v[184:187], v[216:219], v[64:67]
	v_mfma_f32_16x16x32_bf16 v[60:63], v[192:195], v[216:219], v[60:63]
	v_mfma_f32_16x16x32_bf16 v[48:51], v[184:187], v[224:227], v[48:51]
	v_mfma_f32_16x16x32_bf16 v[44:47], v[192:195], v[224:227], v[44:47]
	v_mfma_f32_16x16x32_bf16 v[32:35], v[184:187], v[232:235], v[32:35]
	v_mfma_f32_16x16x32_bf16 v[28:31], v[192:195], v[232:235], v[28:31]
	v_mfma_f32_16x16x32_bf16 v[16:19], v[184:187], v[240:243], v[16:19]
	v_mfma_f32_16x16x32_bf16 v[12:15], v[192:195], v[240:243], v[12:15]
	v_mfma_f32_16x16x32_bf16 v[64:67], v[188:191], v[220:223], v[64:67]
	v_mfma_f32_16x16x32_bf16 v[60:63], v[196:199], v[220:223], v[60:63]
	v_mfma_f32_16x16x32_bf16 v[48:51], v[188:191], v[228:231], v[48:51]
	v_mfma_f32_16x16x32_bf16 v[44:47], v[196:199], v[228:231], v[44:47]
	v_mfma_f32_16x16x32_bf16 v[32:35], v[188:191], v[236:239], v[32:35]
	v_mfma_f32_16x16x32_bf16 v[28:31], v[196:199], v[236:239], v[28:31]
	v_mfma_f32_16x16x32_bf16 v[16:19], v[188:191], v[244:247], v[16:19]
	v_mfma_f32_16x16x32_bf16 v[12:15], v[196:199], v[244:247], v[12:15]
	s_setprio 0
	s_setprio 1
	v_mfma_f32_16x16x32_bf16 v[56:59], v[200:203], v[216:219], v[56:59]
	v_mfma_f32_16x16x32_bf16 v[52:55], v[208:211], v[216:219], v[52:55]
	v_mfma_f32_16x16x32_bf16 v[40:43], v[200:203], v[224:227], v[40:43]
	v_mfma_f32_16x16x32_bf16 v[36:39], v[208:211], v[224:227], v[36:39]
	v_mfma_f32_16x16x32_bf16 v[24:27], v[200:203], v[232:235], v[24:27]
	v_mfma_f32_16x16x32_bf16 v[20:23], v[208:211], v[232:235], v[20:23]
	v_mfma_f32_16x16x32_bf16 v[8:11], v[200:203], v[240:243], v[8:11]
	v_mfma_f32_16x16x32_bf16 v[4:7], v[208:211], v[240:243], v[4:7]
	v_mfma_f32_16x16x32_bf16 v[56:59], v[204:207], v[220:223], v[56:59]
	v_mfma_f32_16x16x32_bf16 v[52:55], v[212:215], v[220:223], v[52:55]
	v_mfma_f32_16x16x32_bf16 v[40:43], v[204:207], v[228:231], v[40:43]
	v_mfma_f32_16x16x32_bf16 v[36:39], v[212:215], v[228:231], v[36:39]
	v_mfma_f32_16x16x32_bf16 v[24:27], v[204:207], v[236:239], v[24:27]
	v_mfma_f32_16x16x32_bf16 v[20:23], v[212:215], v[236:239], v[20:23]
	v_mfma_f32_16x16x32_bf16 v[8:11], v[204:207], v[244:247], v[8:11]
	v_mfma_f32_16x16x32_bf16 v[4:7], v[212:215], v[244:247], v[4:7]
	s_setprio 0
	s_barrier
	s_add_i32 s57, s57, 2
	s_add_u32 s18, s18, 0x100
	s_addc_u32 s19, s19, 0
	s_add_u32 s51, s51, 0x100
	s_addc_u32 s56, s56, 0
	s_cmp_gt_u32 s57, 29
	s_cbranch_scc0 .LBB0_251
	s_and_b64 vcc, exec, s[4:5]
	s_cbranch_vccz .LBB0_254
	s_barrier

; #define PG8_STAGE(bufoff, gbase, voff) do { _Pragma("unroll") for (int _i = 0; _i < 2; ++_i) \
;         __builtin_amdgcn_global_load_lds((const unsigned*)((const char*)(gbase) + (voff)[_i]), (PG8_LAS unsigned*)(lds + (bufoff) + ldsw + _i * 8192), 16, 0, 0); } while (0)
; #define PG8_LDA(dst, b, h) do { _Pragma("unroll") for (int m = 0; m < 4; ++m) _Pragma("unroll") for (int k = 0; k < 2; ++k) dst[m][k] = *(const PG8_LAS bf16x8*)(lds + PG8_SA(b, h) + aoff + m * 2048 + k * 1024); } while (0)
; #define PG8_LDB(dst, b, h) do { _Pragma("unroll") for (int n = 0; n < 2; ++n) _Pragma("unroll") for (int k = 0; k < 2; ++k) dst[n][k] = *(const PG8_LAS bf16x8*)(lds + PG8_SB(b, h) + boff + n * 2048 + k * 1024); } while (0)
; #define PG8_MMA(ai, bj, At, Bt) do { __builtin_amdgcn_s_setprio(1); _Pragma("unroll") for (int m = 0; m < 4; ++m) _Pragma("unroll") for (int n = 0; n < 2; ++n) _Pragma("unroll") for (int k = 0; k < 2; ++k) \
;         acc[ai][bj][m][n] = __builtin_amdgcn_mfma_f32_16x16x32_bf16(Bt[n][k], At[m][k], acc[ai][bj][m][n], 0, 0, 0); __builtin_amdgcn_s_setprio(0); } while (0)
; #define PG8_WAIT_V(n) asm volatile("s_waitcnt vmcnt(" #n ")" ::: "memory")
; #define PG8_WAIT_L(n) asm volatile("s_waitcnt lgkmcnt(" #n ")" ::: "memory")
; template <class Epi, class Sched, bool ALIGN_EPI = false, bool SP2 = false>
; __device__ __forceinline__ void gemm_phase(PG8_LAS unsigned char* lds, const Gemm g, const Sched& S, const Epi& E) {
;     ...
;             const bool last = (t == nt - 2);
;             const char* a1 = cA + (size_t)(t + 1) * kstep;
;             const char* a2 = last ? nA : cA + (size_t)(t + 2) * kstep; const char* b2 = last ? nB : cB + (size_t)(t + 2) * kstep;
;             const char* a3 = a2 + kstep; const char* b3 = b2 + kstep;
;             if (last && has_next) S.a_ready(nxt);
;             if constexpr (SP2) {
;             PG8_LDB(B0, 0, 0); PG8_LDB(B1, 0, 1); PG8_SCHED; PG8_LDA(At, 0, 0); PG8_STAGE(PG8_SA(1, 1), a1 + hstep, voffA);
;             PG8_WAIT_V(8); PG8_WAIT_L(0); PG8_BAR; PG8_MMA(0, 0, At, B0); PG8_MMA(0, 1, At, B1); PG8_BAR; PG8_SCHED;
;             PG8_LDA(At, 0, 1); PG8_STAGE(PG8_SB(0, 0), b2, voffB); PG8_STAGE(PG8_SB(0, 1), b2 + hstep, voffB); PG8_STAGE(PG8_SA(0, 0), a2, voffA);
;             PG8_WAIT_V(8); PG8_WAIT_L(0); PG8_BAR; PG8_MMA(1, 0, At, B0); PG8_MMA(1, 1, At, B1); PG8_BAR; PG8_SCHED;
.LBB0_483:
	s_add_u32 s24, s22, 0xfff80080
	s_addc_u32 s25, s23, -1
	s_add_i32 s65, 0, 0x10000
	s_cmp_eq_u32 s64, 28
	s_cselect_b32 s27, s13, s25
	s_cselect_b32 s26, s19, s24
	s_cselect_b32 s25, s11, s63
	s_cselect_b32 s24, s56, s57
	s_add_i32 s76, 0, 0x14000
	v_add_u32_e32 v162, s65, v185
	v_add_u32_e32 v166, s76, v185
	ds_read_b128 v[132:135], v162
	ds_read_b128 v[136:139], v162 offset:1024
	ds_read_b128 v[158:161], v162 offset:2048
	ds_read_b128 v[162:165], v162 offset:3072
	ds_read_b128 v[188:191], v166
	ds_read_b128 v[192:195], v166 offset:1024
	ds_read_b128 v[196:199], v166 offset:2048
	ds_read_b128 v[200:203], v166 offset:3072
	s_add_i32 m0, s21, 0xc000
	ds_read_b128 v[204:207], v187
	ds_read_b128 v[208:211], v187 offset:1024
	ds_read_b128 v[212:215], v187 offset:2048
	ds_read_b128 v[216:219], v187 offset:3072
	ds_read_b128 v[220:223], v187 offset:4096
	ds_read_b128 v[224:227], v187 offset:5120
	ds_read_b128 v[228:231], v187 offset:6144
	ds_read_b128 v[232:235], v187 offset:7168
	global_load_lds_dwordx4 v154, s[22:23]
	s_add_i32 m0, s21, 0xe000
	s_nop 0
	global_load_lds_dwordx4 v156, s[22:23]
	s_waitcnt vmcnt(8)
	s_waitcnt lgkmcnt(0)
	s_barrier
	s_setprio 1
	s_waitcnt lgkmcnt(0)
	v_mfma_f32_16x16x32_bf16 v[128:131], v[132:135], v[204:207], v[128:131]
	v_mfma_f32_16x16x32_bf16 v[124:127], v[158:161], v[204:207], v[124:127]
	v_mfma_f32_16x16x32_bf16 v[112:115], v[132:135], v[212:215], v[112:115]
	v_mfma_f32_16x16x32_bf16 v[108:111], v[158:161], v[212:215], v[108:111]
	v_mfma_f32_16x16x32_bf16 v[96:99], v[132:135], v[220:223], v[96:99]
	v_mfma_f32_16x16x32_bf16 v[92:95], v[158:161], v[220:223], v[92:95]
	v_mfma_f32_16x16x32_bf16 v[80:83], v[132:135], v[228:231], v[80:83]
	v_mfma_f32_16x16x32_bf16 v[76:79], v[158:161], v[228:231], v[76:79]
	v_mfma_f32_16x16x32_bf16 v[128:131], v[136:139], v[208:211], v[128:131]
	v_mfma_f32_16x16x32_bf16 v[124:127], v[162:165], v[208:211], v[124:127]
	v_mfma_f32_16x16x32_bf16 v[112:115], v[136:139], v[216:219], v[112:115]
	v_mfma_f32_16x16x32_bf16 v[108:111], v[162:165], v[216:219], v[108:111]
	v_mfma_f32_16x16x32_bf16 v[96:99], v[136:139], v[224:227], v[96:99]
	v_mfma_f32_16x16x32_bf16 v[92:95], v[162:165], v[224:227], v[92:95]
	v_mfma_f32_16x16x32_bf16 v[80:83], v[136:139], v[232:235], v[80:83]
	v_mfma_f32_16x16x32_bf16 v[76:79], v[162:165], v[232:235], v[76:79]
	s_setprio 0
	s_setprio 1
	v_mfma_f32_16x16x32_bf16 v[120:123], v[188:191], v[204:207], v[120:123]
	v_mfma_f32_16x16x32_bf16 v[116:119], v[196:199], v[204:207], v[116:119]
	v_mfma_f32_16x16x32_bf16 v[104:107], v[188:191], v[212:215], v[104:107]
	v_mfma_f32_16x16x32_bf16 v[100:103], v[196:199], v[212:215], v[100:103]
	v_mfma_f32_16x16x32_bf16 v[88:91], v[188:191], v[220:223], v[88:91]
	v_mfma_f32_16x16x32_bf16 v[84:87], v[196:199], v[220:223], v[84:87]
	v_mfma_f32_16x16x32_bf16 v[72:75], v[188:191], v[228:231], v[72:75]
	v_mfma_f32_16x16x32_bf16 v[68:71], v[196:199], v[228:231], v[68:71]
	v_mfma_f32_16x16x32_bf16 v[120:123], v[192:195], v[208:211], v[120:123]
	v_mfma_f32_16x16x32_bf16 v[116:119], v[200:203], v[208:211], v[116:119]
	v_mfma_f32_16x16x32_bf16 v[104:107], v[192:195], v[216:219], v[104:107]
	v_mfma_f32_16x16x32_bf16 v[100:103], v[200:203], v[216:219], v[100:103]
	v_mfma_f32_16x16x32_bf16 v[88:91], v[192:195], v[224:227], v[88:91]
	v_mfma_f32_16x16x32_bf16 v[84:87], v[200:203], v[224:227], v[84:87]
	v_mfma_f32_16x16x32_bf16 v[72:75], v[192:195], v[232:235], v[72:75]
	v_mfma_f32_16x16x32_bf16 v[68:71], v[200:203], v[232:235], v[68:71]
	s_setprio 0
	s_barrier
	s_add_i32 s65, s65, s31
	s_mov_b32 m0, s65
	ds_read_b128 v[204:207], v187 offset:16384
	ds_read_b128 v[208:211], v187 offset:17408
	ds_read_b128 v[212:215], v187 offset:18432
	ds_read_b128 v[216:219], v187 offset:19456
	ds_read_b128 v[220:223], v187 offset:20480
	ds_read_b128 v[224:227], v187 offset:21504
	ds_read_b128 v[228:231], v187 offset:22528
	ds_read_b128 v[232:235], v187 offset:23552
	global_load_lds_dwordx4 v2, s[24:25]
	s_add_i32 m0, s65, 0x2000
	s_add_u32 s66, s24, 0x80000
	s_addc_u32 s67, s25, 0
	s_add_i32 s65, s76, s31
	global_load_lds_dwordx4 v152, s[24:25]
	s_mov_b32 m0, s65
	v_lshl_add_u64 v[240:241], s[26:27], 0, v[150:151]
	global_load_lds_dwordx4 v2, s[66:67]
	s_add_i32 m0, s65, 0x2000
	s_nop 0
	global_load_lds_dwordx4 v152, s[66:67]
	v_lshl_add_u64 v[238:239], s[26:27], 0, v[0:1]
	s_mov_b32 m0, s21
	s_nop 0
	global_load_lds_dwordx4 v[238:239], off
	s_mov_b32 m0, s34
	s_nop 0
	global_load_lds_dwordx4 v[240:241], off
	s_waitcnt vmcnt(8)
	s_waitcnt lgkmcnt(0)
	s_barrier
; #define PG8_STAGE(bufoff, gbase, voff) do { _Pragma("unroll") for (int _i = 0; _i < 2; ++_i) \
;         __builtin_amdgcn_global_load_lds((const unsigned*)((const char*)(gbase) + (voff)[_i]), (PG8_LAS unsigned*)(lds + (bufoff) + ldsw + _i * 8192), 16, 0, 0); } while (0)
; #define PG8_LDA(dst, b, h) do { _Pragma("unroll") for (int m = 0; m < 4; ++m) _Pragma("unroll") for (int k = 0; k < 2; ++k) dst[m][k] = *(const PG8_LAS bf16x8*)(lds + PG8_SA(b, h) + aoff + m * 2048 + k * 1024); } while (0)
; #define PG8_LDB(dst, b, h) do { _Pragma("unroll") for (int n = 0; n < 2; ++n) _Pragma("unroll") for (int k = 0; k < 2; ++k) dst[n][k] = *(const PG8_LAS bf16x8*)(lds + PG8_SB(b, h) + boff + n * 2048 + k * 1024); } while (0)
; #define PG8_MMA(ai, bj, At, Bt) do { __builtin_amdgcn_s_setprio(1); _Pragma("unroll") for (int m = 0; m < 4; ++m) _Pragma("unroll") for (int n = 0; n < 2; ++n) _Pragma("unroll") for (int k = 0; k < 2; ++k) \
;         acc[ai][bj][m][n] = __builtin_amdgcn_mfma_f32_16x16x32_bf16(Bt[n][k], At[m][k], acc[ai][bj][m][n], 0, 0, 0); __builtin_amdgcn_s_setprio(0); } while (0)
; #define PG8_WAIT_V(n) asm volatile("s_waitcnt vmcnt(" #n ")" ::: "memory")
; #define PG8_WAIT_L(n) asm volatile("s_waitcnt lgkmcnt(" #n ")" ::: "memory")
; #define PG8_BAR __builtin_amdgcn_s_barrier()
; #define PG8_SCHED __builtin_amdgcn_sched_barrier(0)
; template <class Epi, class Sched, bool ALIGN_EPI = false, bool SP2 = false>
; __device__ __forceinline__ void gemm_phase(PG8_LAS unsigned char* lds, const Gemm g, const Sched& S, const Epi& E) {
;     ...
;             PG8_WAIT_V(8); PG8_WAIT_L(0); PG8_BAR; PG8_MMA(1, 0, At, B0); PG8_MMA(1, 1, At, B1); PG8_BAR; PG8_SCHED;
;             PG8_LDB(B0, 1, 0); PG8_LDB(B1, 1, 1); PG8_SCHED; PG8_LDA(At, 1, 0); PG8_STAGE(PG8_SA(0, 1), a2 + hstep, voffA);
;             PG8_WAIT_V(8); PG8_WAIT_L(0); PG8_BAR; PG8_MMA(0, 0, At, B0); PG8_MMA(0, 1, At, B1); PG8_BAR; PG8_SCHED;
	s_setprio 1
	s_waitcnt lgkmcnt(0)
	v_mfma_f32_16x16x32_bf16 v[64:67], v[132:135], v[204:207], v[64:67]
	v_mfma_f32_16x16x32_bf16 v[60:63], v[158:161], v[204:207], v[60:63]
	v_mfma_f32_16x16x32_bf16 v[48:51], v[132:135], v[212:215], v[48:51]
	v_mfma_f32_16x16x32_bf16 v[44:47], v[158:161], v[212:215], v[44:47]
	v_mfma_f32_16x16x32_bf16 v[32:35], v[132:135], v[220:223], v[32:35]
	v_mfma_f32_16x16x32_bf16 v[28:31], v[158:161], v[220:223], v[28:31]
	v_mfma_f32_16x16x32_bf16 v[16:19], v[132:135], v[228:231], v[16:19]
	v_mfma_f32_16x16x32_bf16 v[12:15], v[158:161], v[228:231], v[12:15]
	v_mfma_f32_16x16x32_bf16 v[64:67], v[136:139], v[208:211], v[64:67]
	v_mfma_f32_16x16x32_bf16 v[60:63], v[162:165], v[208:211], v[60:63]
	v_mfma_f32_16x16x32_bf16 v[48:51], v[136:139], v[216:219], v[48:51]
	v_mfma_f32_16x16x32_bf16 v[44:47], v[162:165], v[216:219], v[44:47]
	v_mfma_f32_16x16x32_bf16 v[32:35], v[136:139], v[224:227], v[32:35]
	v_mfma_f32_16x16x32_bf16 v[28:31], v[162:165], v[224:227], v[28:31]
	v_mfma_f32_16x16x32_bf16 v[16:19], v[136:139], v[232:235], v[16:19]
	v_mfma_f32_16x16x32_bf16 v[12:15], v[162:165], v[232:235], v[12:15]
	s_setprio 0
	s_setprio 1
	v_mfma_f32_16x16x32_bf16 v[56:59], v[188:191], v[204:207], v[56:59]
	v_mfma_f32_16x16x32_bf16 v[52:55], v[196:199], v[204:207], v[52:55]
	v_mfma_f32_16x16x32_bf16 v[40:43], v[188:191], v[212:215], v[40:43]
	v_mfma_f32_16x16x32_bf16 v[36:39], v[196:199], v[212:215], v[36:39]
	v_mfma_f32_16x16x32_bf16 v[24:27], v[188:191], v[220:223], v[24:27]
	v_mfma_f32_16x16x32_bf16 v[20:23], v[196:199], v[220:223], v[20:23]
	v_mfma_f32_16x16x32_bf16 v[8:11], v[188:191], v[228:231], v[8:11]
	v_mfma_f32_16x16x32_bf16 v[4:7], v[196:199], v[228:231], v[4:7]
	v_mfma_f32_16x16x32_bf16 v[56:59], v[192:195], v[208:211], v[56:59]
	v_mfma_f32_16x16x32_bf16 v[52:55], v[200:203], v[208:211], v[52:55]
	v_mfma_f32_16x16x32_bf16 v[40:43], v[192:195], v[216:219], v[40:43]
	v_mfma_f32_16x16x32_bf16 v[36:39], v[200:203], v[216:219], v[36:39]
	v_mfma_f32_16x16x32_bf16 v[24:27], v[192:195], v[224:227], v[24:27]
	v_mfma_f32_16x16x32_bf16 v[20:23], v[200:203], v[224:227], v[20:23]
	v_mfma_f32_16x16x32_bf16 v[8:11], v[192:195], v[232:235], v[8:11]
	v_mfma_f32_16x16x32_bf16 v[4:7], v[200:203], v[232:235], v[4:7]
	s_setprio 0
	s_barrier
	s_add_i32 s65, 0, 0x18000
	s_add_i32 s66, 0, 0x1c000
	v_add_u32_e32 v162, s65, v185
	v_add_u32_e32 v200, s66, v185
	ds_read_b128 v[132:135], v162
	ds_read_b128 v[136:139], v162 offset:1024
	ds_read_b128 v[158:161], v162 offset:2048
	ds_read_b128 v[162:165], v162 offset:3072
	ds_read_b128 v[188:191], v200
	ds_read_b128 v[192:195], v200 offset:1024
	ds_read_b128 v[196:199], v200 offset:2048
	ds_read_b128 v[200:203], v200 offset:3072
	s_add_u32 s26, s26, 0x80000
	s_addc_u32 s27, s27, 0
	s_mov_b32 m0, s35
	ds_read_b128 v[204:207], v187 offset:32768
	ds_read_b128 v[208:211], v187 offset:33792
	ds_read_b128 v[212:215], v187 offset:34816
	ds_read_b128 v[216:219], v187 offset:35840
	ds_read_b128 v[220:223], v187 offset:36864
	ds_read_b128 v[224:227], v187 offset:37888
	ds_read_b128 v[228:231], v187 offset:38912
	ds_read_b128 v[232:235], v187 offset:39936
	global_load_lds_dwordx4 v0, s[26:27]
	s_mov_b32 m0, s42
	s_nop 0
	global_load_lds_dwordx4 v150, s[26:27]
	s_waitcnt vmcnt(8)
	s_waitcnt lgkmcnt(0)
	s_barrier
	s_setprio 1
	s_waitcnt lgkmcnt(0)
	v_mfma_f32_16x16x32_bf16 v[128:131], v[132:135], v[204:207], v[128:131]
	v_mfma_f32_16x16x32_bf16 v[124:127], v[158:161], v[204:207], v[124:127]
	v_mfma_f32_16x16x32_bf16 v[112:115], v[132:135], v[212:215], v[112:115]
	v_mfma_f32_16x16x32_bf16 v[108:111], v[158:161], v[212:215], v[108:111]
	v_mfma_f32_16x16x32_bf16 v[96:99], v[132:135], v[220:223], v[96:99]
	v_mfma_f32_16x16x32_bf16 v[92:95], v[158:161], v[220:223], v[92:95]
	v_mfma_f32_16x16x32_bf16 v[80:83], v[132:135], v[228:231], v[80:83]
	v_mfma_f32_16x16x32_bf16 v[76:79], v[158:161], v[228:231], v[76:79]
	v_mfma_f32_16x16x32_bf16 v[128:131], v[136:139], v[208:211], v[128:131]
	v_mfma_f32_16x16x32_bf16 v[124:127], v[162:165], v[208:211], v[124:127]
	v_mfma_f32_16x16x32_bf16 v[112:115], v[136:139], v[216:219], v[112:115]
	v_mfma_f32_16x16x32_bf16 v[108:111], v[162:165], v[216:219], v[108:111]
	v_mfma_f32_16x16x32_bf16 v[96:99], v[136:139], v[224:227], v[96:99]
	v_mfma_f32_16x16x32_bf16 v[92:95], v[162:165], v[224:227], v[92:95]
	v_mfma_f32_16x16x32_bf16 v[80:83], v[136:139], v[232:235], v[80:83]
	v_mfma_f32_16x16x32_bf16 v[76:79], v[162:165], v[232:235], v[76:79]
	s_setprio 0
	s_setprio 1
	v_mfma_f32_16x16x32_bf16 v[120:123], v[188:191], v[204:207], v[120:123]
	v_mfma_f32_16x16x32_bf16 v[116:119], v[196:199], v[204:207], v[116:119]
	v_mfma_f32_16x16x32_bf16 v[104:107], v[188:191], v[212:215], v[104:107]
	v_mfma_f32_16x16x32_bf16 v[100:103], v[196:199], v[212:215], v[100:103]
	v_mfma_f32_16x16x32_bf16 v[88:91], v[188:191], v[220:223], v[88:91]
	v_mfma_f32_16x16x32_bf16 v[84:87], v[196:199], v[220:223], v[84:87]
	v_mfma_f32_16x16x32_bf16 v[72:75], v[188:191], v[228:231], v[72:75]
	v_mfma_f32_16x16x32_bf16 v[68:71], v[196:199], v[228:231], v[68:71]
	v_mfma_f32_16x16x32_bf16 v[120:123], v[192:195], v[208:211], v[120:123]
	v_mfma_f32_16x16x32_bf16 v[116:119], v[200:203], v[208:211], v[116:119]
	v_mfma_f32_16x16x32_bf16 v[104:107], v[192:195], v[216:219], v[104:107]
	v_mfma_f32_16x16x32_bf16 v[100:103], v[200:203], v[216:219], v[100:103]
	v_mfma_f32_16x16x32_bf16 v[88:91], v[192:195], v[224:227], v[88:91]
	v_mfma_f32_16x16x32_bf16 v[84:87], v[200:203], v[224:227], v[84:87]
	v_mfma_f32_16x16x32_bf16 v[72:75], v[192:195], v[232:235], v[72:75]
	v_mfma_f32_16x16x32_bf16 v[68:71], v[200:203], v[232:235], v[68:71]
	s_setprio 0
	s_barrier
; #define PG8_STAGE(bufoff, gbase, voff) do { _Pragma("unroll") for (int _i = 0; _i < 2; ++_i) \
;         __builtin_amdgcn_global_load_lds((const unsigned*)((const char*)(gbase) + (voff)[_i]), (PG8_LAS unsigned*)(lds + (bufoff) + ldsw + _i * 8192), 16, 0, 0); } while (0)
; #define PG8_LDA(dst, b, h) do { _Pragma("unroll") for (int m = 0; m < 4; ++m) _Pragma("unroll") for (int k = 0; k < 2; ++k) dst[m][k] = *(const PG8_LAS bf16x8*)(lds + PG8_SA(b, h) + aoff + m * 2048 + k * 1024); } while (0)
; #define PG8_MMA(ai, bj, At, Bt) do { __builtin_amdgcn_s_setprio(1); _Pragma("unroll") for (int m = 0; m < 4; ++m) _Pragma("unroll") for (int n = 0; n < 2; ++n) _Pragma("unroll") for (int k = 0; k < 2; ++k) \
;         acc[ai][bj][m][n] = __builtin_amdgcn_mfma_f32_16x16x32_bf16(Bt[n][k], At[m][k], acc[ai][bj][m][n], 0, 0, 0); __builtin_amdgcn_s_setprio(0); } while (0)
; #define PG8_WAIT_V(n) asm volatile("s_waitcnt vmcnt(" #n ")" ::: "memory")
; #define PG8_WAIT_L(n) asm volatile("s_waitcnt lgkmcnt(" #n ")" ::: "memory")
; #define PG8_BAR __builtin_amdgcn_s_barrier()
; #define PG8_SCHED __builtin_amdgcn_sched_barrier(0)
; template <class Epi, class Sched, bool ALIGN_EPI = false, bool SP2 = false>
; __device__ __forceinline__ void gemm_phase(PG8_LAS unsigned char* lds, const Gemm g, const Sched& S, const Epi& E) {
;     ...
;             PG8_LDA(At, 1, 1); PG8_STAGE(PG8_SB(1, 0), b3, voffB); PG8_STAGE(PG8_SB(1, 1), b3 + hstep, voffB); PG8_STAGE(PG8_SA(1, 0), a3, voffA);
;             PG8_WAIT_V(8); PG8_WAIT_L(0); PG8_BAR; PG8_MMA(1, 0, At, B0); PG8_MMA(1, 1, At, B1); PG8_BAR; PG8_SCHED;
;     ...
;         if constexpr (ALIGN_EPI) { if (wr == 0) PG8_BAR; }
	s_add_i32 s26, s65, s31
	s_mov_b32 m0, s26
	ds_read_b128 v[204:207], v187 offset:49152
	ds_read_b128 v[208:211], v187 offset:50176
	ds_read_b128 v[212:215], v187 offset:51200
	ds_read_b128 v[216:219], v187 offset:52224
	ds_read_b128 v[220:223], v187 offset:53248
	ds_read_b128 v[224:227], v187 offset:54272
	ds_read_b128 v[228:231], v187 offset:55296
	ds_read_b128 v[232:235], v187 offset:56320
	s_add_u32 vcc_lo, s24, 0x80
	s_addc_u32 vcc_hi, s25, 0
	global_load_lds_dwordx4 v2, vcc
	s_add_i32 m0, s26, 0x2000
	s_add_u32 s24, s24, 0x80080
	s_addc_u32 s25, s25, 0
	s_add_i32 s26, s66, s31
	s_add_u32 vcc_lo, s24, 0xfff80000
	s_addc_u32 vcc_hi, s25, -1
	global_load_lds_dwordx4 v152, vcc
	s_mov_b32 m0, s26
	s_nop 0
	global_load_lds_dwordx4 v2, s[24:25]
	s_add_i32 m0, s26, 0x2000
	s_nop 0
	global_load_lds_dwordx4 v152, s[24:25]
	v_lshl_add_u64 v[166:167], v[238:239], 0, s[36:37]
	s_mov_b32 m0, s44
	s_nop 0
	global_load_lds_dwordx4 v[166:167], off
	v_lshl_add_u64 v[166:167], v[240:241], 0, s[36:37]
	s_mov_b32 m0, s45
	s_nop 0
	global_load_lds_dwordx4 v[166:167], off
	s_waitcnt vmcnt(8)
	s_waitcnt lgkmcnt(0)
	s_barrier
	s_setprio 1
	s_waitcnt lgkmcnt(0)
	v_mfma_f32_16x16x32_bf16 v[64:67], v[132:135], v[204:207], v[64:67]
	v_mfma_f32_16x16x32_bf16 v[60:63], v[158:161], v[204:207], v[60:63]
	v_mfma_f32_16x16x32_bf16 v[48:51], v[132:135], v[212:215], v[48:51]
	v_mfma_f32_16x16x32_bf16 v[44:47], v[158:161], v[212:215], v[44:47]
	v_mfma_f32_16x16x32_bf16 v[32:35], v[132:135], v[220:223], v[32:35]
	v_mfma_f32_16x16x32_bf16 v[28:31], v[158:161], v[220:223], v[28:31]
	v_mfma_f32_16x16x32_bf16 v[16:19], v[132:135], v[228:231], v[16:19]
	v_mfma_f32_16x16x32_bf16 v[12:15], v[158:161], v[228:231], v[12:15]
	v_mfma_f32_16x16x32_bf16 v[64:67], v[136:139], v[208:211], v[64:67]
	v_mfma_f32_16x16x32_bf16 v[60:63], v[162:165], v[208:211], v[60:63]
	v_mfma_f32_16x16x32_bf16 v[48:51], v[136:139], v[216:219], v[48:51]
	v_mfma_f32_16x16x32_bf16 v[44:47], v[162:165], v[216:219], v[44:47]
	v_mfma_f32_16x16x32_bf16 v[32:35], v[136:139], v[224:227], v[32:35]
	v_mfma_f32_16x16x32_bf16 v[28:31], v[162:165], v[224:227], v[28:31]
	v_mfma_f32_16x16x32_bf16 v[16:19], v[136:139], v[232:235], v[16:19]
	v_mfma_f32_16x16x32_bf16 v[12:15], v[162:165], v[232:235], v[12:15]
	s_setprio 0
	s_setprio 1
	v_mfma_f32_16x16x32_bf16 v[56:59], v[188:191], v[204:207], v[56:59]
	v_mfma_f32_16x16x32_bf16 v[52:55], v[196:199], v[204:207], v[52:55]
	v_mfma_f32_16x16x32_bf16 v[40:43], v[188:191], v[212:215], v[40:43]
	v_mfma_f32_16x16x32_bf16 v[36:39], v[196:199], v[212:215], v[36:39]
	v_mfma_f32_16x16x32_bf16 v[24:27], v[188:191], v[220:223], v[24:27]
	v_mfma_f32_16x16x32_bf16 v[20:23], v[196:199], v[220:223], v[20:23]
	v_mfma_f32_16x16x32_bf16 v[8:11], v[188:191], v[228:231], v[8:11]
	v_mfma_f32_16x16x32_bf16 v[4:7], v[196:199], v[228:231], v[4:7]
	v_mfma_f32_16x16x32_bf16 v[56:59], v[192:195], v[208:211], v[56:59]
	v_mfma_f32_16x16x32_bf16 v[52:55], v[200:203], v[208:211], v[52:55]
	v_mfma_f32_16x16x32_bf16 v[40:43], v[192:195], v[216:219], v[40:43]
	v_mfma_f32_16x16x32_bf16 v[36:39], v[200:203], v[216:219], v[36:39]
	v_mfma_f32_16x16x32_bf16 v[24:27], v[192:195], v[224:227], v[24:27]
	v_mfma_f32_16x16x32_bf16 v[20:23], v[200:203], v[224:227], v[20:23]
	v_mfma_f32_16x16x32_bf16 v[8:11], v[192:195], v[232:235], v[8:11]
	v_mfma_f32_16x16x32_bf16 v[4:7], v[200:203], v[232:235], v[4:7]
	s_setprio 0
	s_barrier
	s_add_i32 s64, s64, 2
	s_add_u32 s22, s22, 0x100
	s_addc_u32 s23, s23, 0
	s_add_u32 s57, s57, 0x100
	s_addc_u32 s63, s63, 0
	s_cmp_gt_u32 s64, 29
	s_cbranch_scc0 .LBB0_483
	s_and_b64 vcc, exec, s[8:9]
	s_cbranch_vccz .LBB0_486
	s_barrier

; #define PG8_STAGE(bufoff, gbase, voff) do { _Pragma("unroll") for (int _i = 0; _i < 2; ++_i) \
;         __builtin_amdgcn_global_load_lds((const unsigned*)((const char*)(gbase) + (voff)[_i]), (PG8_LAS unsigned*)(lds + (bufoff) + ldsw + _i * 8192), 16, 0, 0); } while (0)
; #define PG8_LDA(dst, b, h) do { _Pragma("unroll") for (int m = 0; m < 4; ++m) _Pragma("unroll") for (int k = 0; k < 2; ++k) dst[m][k] = *(const PG8_LAS bf16x8*)(lds + PG8_SA(b, h) + aoff + m * 2048 + k * 1024); } while (0)
; #define PG8_LDB(dst, b, h) do { _Pragma("unroll") for (int n = 0; n < 2; ++n) _Pragma("unroll") for (int k = 0; k < 2; ++k) dst[n][k] = *(const PG8_LAS bf16x8*)(lds + PG8_SB(b, h) + boff + n * 2048 + k * 1024); } while (0)
; #define PG8_MMA(ai, bj, At, Bt) do { __builtin_amdgcn_s_setprio(1); _Pragma("unroll") for (int m = 0; m < 4; ++m) _Pragma("unroll") for (int n = 0; n < 2; ++n) _Pragma("unroll") for (int k = 0; k < 2; ++k) \
;         acc[ai][bj][m][n] = __builtin_amdgcn_mfma_f32_16x16x32_bf16(Bt[n][k], At[m][k], acc[ai][bj][m][n], 0, 0, 0); __builtin_amdgcn_s_setprio(0); } while (0)
; #define PG8_WAIT_V(n) asm volatile("s_waitcnt vmcnt(" #n ")" ::: "memory")
; #define PG8_WAIT_L(n) asm volatile("s_waitcnt lgkmcnt(" #n ")" ::: "memory")
; #define PG8_BAR __builtin_amdgcn_s_barrier()
; #define PG8_SCHED __builtin_amdgcn_sched_barrier(0)
; template <class Epi, class Sched, bool ALIGN_EPI = false, bool SP2 = false>
; __device__ __forceinline__ void gemm_phase(PG8_LAS unsigned char* lds, const Gemm g, const Sched& S, const Epi& E) {
;     ...
;             const bool last = (t == nt - 2);
;             const char* a1 = cA + (size_t)(t + 1) * kstep;
;             const char* a2 = last ? nA : cA + (size_t)(t + 2) * kstep; const char* b2 = last ? nB : cB + (size_t)(t + 2) * kstep;
;             const char* a3 = a2 + kstep; const char* b3 = b2 + kstep;
;             if (last && has_next) S.a_ready(nxt);
;             if constexpr (SP2) {
;             PG8_LDB(B0, 0, 0); PG8_LDB(B1, 0, 1); PG8_SCHED; PG8_LDA(At, 0, 0); PG8_STAGE(PG8_SA(1, 1), a1 + hstep, voffA);
;             PG8_WAIT_V(8); PG8_WAIT_L(0); PG8_BAR; PG8_MMA(0, 0, At, B0); PG8_MMA(0, 1, At, B1); PG8_BAR; PG8_SCHED;
;             PG8_LDA(At, 0, 1); PG8_STAGE(PG8_SB(0, 0), b2, voffB); PG8_STAGE(PG8_SB(0, 1), b2 + hstep, voffB); PG8_STAGE(PG8_SA(0, 0), a2, voffA);
.LBB0_567:
	s_add_u32 s20, s18, 0xfff80080
	s_addc_u32 s21, s19, -1
	s_add_i32 s63, 0, 0x10000
	s_cmp_eq_u32 s57, 28
	s_cselect_b32 s23, s11, s21
	s_cselect_b32 s22, s45, s20
	v_add_u32_e32 v150, s63, v153
	s_cselect_b32 s21, s9, s56
	s_cselect_b32 s20, s50, s51
	s_add_i32 s66, 0, 0x14000
	ds_read_b128 v[184:187], v150
	ds_read_b128 v[188:191], v150 offset:1024
	ds_read_b128 v[192:195], v150 offset:2048
	ds_read_b128 v[196:199], v150 offset:3072
	v_add_u32_e32 v150, s66, v153
	ds_read_b128 v[200:203], v150
	ds_read_b128 v[204:207], v150 offset:1024
	ds_read_b128 v[208:211], v150 offset:2048
	ds_read_b128 v[212:215], v150 offset:3072
	s_add_i32 m0, s29, 0xc000
	ds_read_b128 v[216:219], v155
	ds_read_b128 v[220:223], v155 offset:1024
	ds_read_b128 v[224:227], v155 offset:2048
	ds_read_b128 v[228:231], v155 offset:3072
	ds_read_b128 v[232:235], v155 offset:4096
	ds_read_b128 v[236:239], v155 offset:5120
	ds_read_b128 v[240:243], v155 offset:6144
	ds_read_b128 v[244:247], v155 offset:7168
	global_load_lds_dwordx4 v136, s[18:19]
	s_add_i32 m0, s29, 0xe000
	s_nop 0
	global_load_lds_dwordx4 v138, s[18:19]
	s_waitcnt vmcnt(8)
	s_waitcnt lgkmcnt(0)
	s_barrier
	s_setprio 1
	s_waitcnt lgkmcnt(0)
	v_mfma_f32_16x16x32_bf16 v[128:131], v[184:187], v[216:219], v[128:131]
	v_mfma_f32_16x16x32_bf16 v[120:123], v[192:195], v[216:219], v[120:123]
	v_mfma_f32_16x16x32_bf16 v[112:115], v[184:187], v[224:227], v[112:115]
	v_mfma_f32_16x16x32_bf16 v[104:107], v[192:195], v[224:227], v[104:107]
	v_mfma_f32_16x16x32_bf16 v[96:99], v[184:187], v[232:235], v[96:99]
	v_mfma_f32_16x16x32_bf16 v[88:91], v[192:195], v[232:235], v[88:91]
	v_mfma_f32_16x16x32_bf16 v[80:83], v[184:187], v[240:243], v[80:83]
	v_mfma_f32_16x16x32_bf16 v[72:75], v[192:195], v[240:243], v[72:75]
	v_mfma_f32_16x16x32_bf16 v[128:131], v[188:191], v[220:223], v[128:131]
	v_mfma_f32_16x16x32_bf16 v[120:123], v[196:199], v[220:223], v[120:123]
	v_mfma_f32_16x16x32_bf16 v[112:115], v[188:191], v[228:231], v[112:115]
	v_mfma_f32_16x16x32_bf16 v[104:107], v[196:199], v[228:231], v[104:107]
	v_mfma_f32_16x16x32_bf16 v[96:99], v[188:191], v[236:239], v[96:99]
	v_mfma_f32_16x16x32_bf16 v[88:91], v[196:199], v[236:239], v[88:91]
	v_mfma_f32_16x16x32_bf16 v[80:83], v[188:191], v[244:247], v[80:83]
	v_mfma_f32_16x16x32_bf16 v[72:75], v[196:199], v[244:247], v[72:75]
	s_setprio 0
	s_setprio 1
	v_mfma_f32_16x16x32_bf16 v[124:127], v[200:203], v[216:219], v[124:127]
	v_mfma_f32_16x16x32_bf16 v[116:119], v[208:211], v[216:219], v[116:119]
	v_mfma_f32_16x16x32_bf16 v[108:111], v[200:203], v[224:227], v[108:111]
	v_mfma_f32_16x16x32_bf16 v[100:103], v[208:211], v[224:227], v[100:103]
	v_mfma_f32_16x16x32_bf16 v[92:95], v[200:203], v[232:235], v[92:95]
	v_mfma_f32_16x16x32_bf16 v[84:87], v[208:211], v[232:235], v[84:87]
	v_mfma_f32_16x16x32_bf16 v[76:79], v[200:203], v[240:243], v[76:79]
	v_mfma_f32_16x16x32_bf16 v[68:71], v[208:211], v[240:243], v[68:71]
	v_mfma_f32_16x16x32_bf16 v[124:127], v[204:207], v[220:223], v[124:127]
	v_mfma_f32_16x16x32_bf16 v[116:119], v[212:215], v[220:223], v[116:119]
	v_mfma_f32_16x16x32_bf16 v[108:111], v[204:207], v[228:231], v[108:111]
	v_mfma_f32_16x16x32_bf16 v[100:103], v[212:215], v[228:231], v[100:103]
	v_mfma_f32_16x16x32_bf16 v[92:95], v[204:207], v[236:239], v[92:95]
	v_mfma_f32_16x16x32_bf16 v[84:87], v[212:215], v[236:239], v[84:87]
	v_mfma_f32_16x16x32_bf16 v[76:79], v[204:207], v[244:247], v[76:79]
	v_mfma_f32_16x16x32_bf16 v[68:71], v[212:215], v[244:247], v[68:71]
	s_setprio 0
	s_barrier
	s_add_i32 s63, s63, s27
	s_mov_b32 m0, s63
	ds_read_b128 v[216:219], v155 offset:16384
	ds_read_b128 v[220:223], v155 offset:17408
	ds_read_b128 v[224:227], v155 offset:18432
	ds_read_b128 v[228:231], v155 offset:19456
	ds_read_b128 v[232:235], v155 offset:20480
	ds_read_b128 v[236:239], v155 offset:21504
	ds_read_b128 v[240:243], v155 offset:22528
	ds_read_b128 v[244:247], v155 offset:23552
	global_load_lds_dwordx4 v2, s[20:21]
	s_add_i32 m0, s63, 0x2000
	s_add_u32 s64, s20, 0x80000
	s_addc_u32 s65, s21, 0
	s_add_i32 s63, s66, s27
	global_load_lds_dwordx4 v0, s[20:21]
	s_mov_b32 m0, s63
	v_lshl_add_u64 v[250:251], s[22:23], 0, v[132:133]
	global_load_lds_dwordx4 v2, s[64:65]
	s_add_i32 m0, s63, 0x2000
	s_nop 0
	global_load_lds_dwordx4 v0, s[64:65]
	v_lshl_add_u64 v[248:249], s[22:23], 0, v[134:135]
	s_mov_b32 m0, s29
	s_nop 0
	global_load_lds_dwordx4 v[248:249], off
	s_mov_b32 m0, s30
	s_nop 0
	global_load_lds_dwordx4 v[250:251], off
	s_waitcnt vmcnt(8)
	s_waitcnt lgkmcnt(0)
	s_barrier
; #define PG8_STAGE(bufoff, gbase, voff) do { _Pragma("unroll") for (int _i = 0; _i < 2; ++_i) \
;         __builtin_amdgcn_global_load_lds((const unsigned*)((const char*)(gbase) + (voff)[_i]), (PG8_LAS unsigned*)(lds + (bufoff) + ldsw + _i * 8192), 16, 0, 0); } while (0)
; #define PG8_LDA(dst, b, h) do { _Pragma("unroll") for (int m = 0; m < 4; ++m) _Pragma("unroll") for (int k = 0; k < 2; ++k) dst[m][k] = *(const PG8_LAS bf16x8*)(lds + PG8_SA(b, h) + aoff + m * 2048 + k * 1024); } while (0)
; #define PG8_LDB(dst, b, h) do { _Pragma("unroll") for (int n = 0; n < 2; ++n) _Pragma("unroll") for (int k = 0; k < 2; ++k) dst[n][k] = *(const PG8_LAS bf16x8*)(lds + PG8_SB(b, h) + boff + n * 2048 + k * 1024); } while (0)
; #define PG8_MMA(ai, bj, At, Bt) do { __builtin_amdgcn_s_setprio(1); _Pragma("unroll") for (int m = 0; m < 4; ++m) _Pragma("unroll") for (int n = 0; n < 2; ++n) _Pragma("unroll") for (int k = 0; k < 2; ++k) \
;         acc[ai][bj][m][n] = __builtin_amdgcn_mfma_f32_16x16x32_bf16(Bt[n][k], At[m][k], acc[ai][bj][m][n], 0, 0, 0); __builtin_amdgcn_s_setprio(0); } while (0)
; #define PG8_WAIT_V(n) asm volatile("s_waitcnt vmcnt(" #n ")" ::: "memory")
; #define PG8_WAIT_L(n) asm volatile("s_waitcnt lgkmcnt(" #n ")" ::: "memory")
; #define PG8_BAR __builtin_amdgcn_s_barrier()
; #define PG8_SCHED __builtin_amdgcn_sched_barrier(0)
; template <class Epi, class Sched, bool ALIGN_EPI = false, bool SP2 = false>
; __device__ __forceinline__ void gemm_phase(PG8_LAS unsigned char* lds, const Gemm g, const Sched& S, const Epi& E) {
;     ...
;             PG8_WAIT_V(8); PG8_WAIT_L(0); PG8_BAR; PG8_MMA(1, 0, At, B0); PG8_MMA(1, 1, At, B1); PG8_BAR; PG8_SCHED;
;             PG8_LDB(B0, 1, 0); PG8_LDB(B1, 1, 1); PG8_SCHED; PG8_LDA(At, 1, 0); PG8_STAGE(PG8_SA(0, 1), a2 + hstep, voffA);
;             PG8_WAIT_V(8); PG8_WAIT_L(0); PG8_BAR; PG8_MMA(0, 0, At, B0); PG8_MMA(0, 1, At, B1); PG8_BAR; PG8_SCHED;
	s_setprio 1
	s_waitcnt lgkmcnt(0)
	v_mfma_f32_16x16x32_bf16 v[64:67], v[184:187], v[216:219], v[64:67]
	v_mfma_f32_16x16x32_bf16 v[56:59], v[192:195], v[216:219], v[56:59]
	v_mfma_f32_16x16x32_bf16 v[48:51], v[184:187], v[224:227], v[48:51]
	v_mfma_f32_16x16x32_bf16 v[40:43], v[192:195], v[224:227], v[40:43]
	v_mfma_f32_16x16x32_bf16 v[32:35], v[184:187], v[232:235], v[32:35]
	v_mfma_f32_16x16x32_bf16 v[24:27], v[192:195], v[232:235], v[24:27]
	v_mfma_f32_16x16x32_bf16 v[16:19], v[184:187], v[240:243], v[16:19]
	v_mfma_f32_16x16x32_bf16 v[8:11], v[192:195], v[240:243], v[8:11]
	v_mfma_f32_16x16x32_bf16 v[64:67], v[188:191], v[220:223], v[64:67]
	v_mfma_f32_16x16x32_bf16 v[56:59], v[196:199], v[220:223], v[56:59]
	v_mfma_f32_16x16x32_bf16 v[48:51], v[188:191], v[228:231], v[48:51]
	v_mfma_f32_16x16x32_bf16 v[40:43], v[196:199], v[228:231], v[40:43]
	v_mfma_f32_16x16x32_bf16 v[32:35], v[188:191], v[236:239], v[32:35]
	v_mfma_f32_16x16x32_bf16 v[24:27], v[196:199], v[236:239], v[24:27]
	v_mfma_f32_16x16x32_bf16 v[16:19], v[188:191], v[244:247], v[16:19]
	v_mfma_f32_16x16x32_bf16 v[8:11], v[196:199], v[244:247], v[8:11]
	s_setprio 0
	s_setprio 1
	v_mfma_f32_16x16x32_bf16 v[60:63], v[200:203], v[216:219], v[60:63]
	v_mfma_f32_16x16x32_bf16 v[52:55], v[208:211], v[216:219], v[52:55]
	v_mfma_f32_16x16x32_bf16 v[44:47], v[200:203], v[224:227], v[44:47]
	v_mfma_f32_16x16x32_bf16 v[36:39], v[208:211], v[224:227], v[36:39]
	v_mfma_f32_16x16x32_bf16 v[28:31], v[200:203], v[232:235], v[28:31]
	v_mfma_f32_16x16x32_bf16 v[20:23], v[208:211], v[232:235], v[20:23]
	v_mfma_f32_16x16x32_bf16 v[12:15], v[200:203], v[240:243], v[12:15]
	v_mfma_f32_16x16x32_bf16 v[4:7], v[208:211], v[240:243], v[4:7]
	v_mfma_f32_16x16x32_bf16 v[60:63], v[204:207], v[220:223], v[60:63]
	v_mfma_f32_16x16x32_bf16 v[52:55], v[212:215], v[220:223], v[52:55]
	v_mfma_f32_16x16x32_bf16 v[44:47], v[204:207], v[228:231], v[44:47]
	v_mfma_f32_16x16x32_bf16 v[36:39], v[212:215], v[228:231], v[36:39]
	v_mfma_f32_16x16x32_bf16 v[28:31], v[204:207], v[236:239], v[28:31]
	v_mfma_f32_16x16x32_bf16 v[20:23], v[212:215], v[236:239], v[20:23]
	v_mfma_f32_16x16x32_bf16 v[12:15], v[204:207], v[244:247], v[12:15]
	v_mfma_f32_16x16x32_bf16 v[4:7], v[212:215], v[244:247], v[4:7]
	s_setprio 0
	s_barrier
	s_add_i32 s63, 0, 0x18000
	v_add_u32_e32 v161, s63, v153
	s_add_i32 s64, 0, 0x1c000
	ds_read_b128 v[184:187], v161
	ds_read_b128 v[188:191], v161 offset:1024
	ds_read_b128 v[192:195], v161 offset:2048
	ds_read_b128 v[196:199], v161 offset:3072
	v_add_u32_e32 v161, s64, v153
	ds_read_b128 v[200:203], v161
	ds_read_b128 v[204:207], v161 offset:1024
	ds_read_b128 v[208:211], v161 offset:2048
	ds_read_b128 v[212:215], v161 offset:3072
	s_add_u32 s22, s22, 0x80000
	s_addc_u32 s23, s23, 0
	s_mov_b32 m0, s31
	ds_read_b128 v[216:219], v155 offset:32768
	ds_read_b128 v[220:223], v155 offset:33792
	ds_read_b128 v[224:227], v155 offset:34816
	ds_read_b128 v[228:231], v155 offset:35840
	ds_read_b128 v[232:235], v155 offset:36864
	ds_read_b128 v[236:239], v155 offset:37888
	ds_read_b128 v[240:243], v155 offset:38912
	ds_read_b128 v[244:247], v155 offset:39936
	global_load_lds_dwordx4 v134, s[22:23]
	s_mov_b32 m0, s34
	s_nop 0
	global_load_lds_dwordx4 v132, s[22:23]
	s_waitcnt vmcnt(8)
	s_waitcnt lgkmcnt(0)
	s_barrier
	s_setprio 1
	s_waitcnt lgkmcnt(0)
	v_mfma_f32_16x16x32_bf16 v[128:131], v[184:187], v[216:219], v[128:131]
	v_mfma_f32_16x16x32_bf16 v[120:123], v[192:195], v[216:219], v[120:123]
	v_mfma_f32_16x16x32_bf16 v[112:115], v[184:187], v[224:227], v[112:115]
	v_mfma_f32_16x16x32_bf16 v[104:107], v[192:195], v[224:227], v[104:107]
	v_mfma_f32_16x16x32_bf16 v[96:99], v[184:187], v[232:235], v[96:99]
	v_mfma_f32_16x16x32_bf16 v[88:91], v[192:195], v[232:235], v[88:91]
	v_mfma_f32_16x16x32_bf16 v[80:83], v[184:187], v[240:243], v[80:83]
	v_mfma_f32_16x16x32_bf16 v[72:75], v[192:195], v[240:243], v[72:75]
	v_mfma_f32_16x16x32_bf16 v[128:131], v[188:191], v[220:223], v[128:131]
	v_mfma_f32_16x16x32_bf16 v[120:123], v[196:199], v[220:223], v[120:123]
	v_mfma_f32_16x16x32_bf16 v[112:115], v[188:191], v[228:231], v[112:115]
	v_mfma_f32_16x16x32_bf16 v[104:107], v[196:199], v[228:231], v[104:107]
	v_mfma_f32_16x16x32_bf16 v[96:99], v[188:191], v[236:239], v[96:99]
	v_mfma_f32_16x16x32_bf16 v[88:91], v[196:199], v[236:239], v[88:91]
	v_mfma_f32_16x16x32_bf16 v[80:83], v[188:191], v[244:247], v[80:83]
	v_mfma_f32_16x16x32_bf16 v[72:75], v[196:199], v[244:247], v[72:75]
	s_setprio 0
	s_setprio 1
	v_mfma_f32_16x16x32_bf16 v[124:127], v[200:203], v[216:219], v[124:127]
	v_mfma_f32_16x16x32_bf16 v[116:119], v[208:211], v[216:219], v[116:119]
	v_mfma_f32_16x16x32_bf16 v[108:111], v[200:203], v[224:227], v[108:111]
	v_mfma_f32_16x16x32_bf16 v[100:103], v[208:211], v[224:227], v[100:103]
	v_mfma_f32_16x16x32_bf16 v[92:95], v[200:203], v[232:235], v[92:95]
	v_mfma_f32_16x16x32_bf16 v[84:87], v[208:211], v[232:235], v[84:87]
	v_mfma_f32_16x16x32_bf16 v[76:79], v[200:203], v[240:243], v[76:79]
	v_mfma_f32_16x16x32_bf16 v[68:71], v[208:211], v[240:243], v[68:71]
	v_mfma_f32_16x16x32_bf16 v[124:127], v[204:207], v[220:223], v[124:127]
	v_mfma_f32_16x16x32_bf16 v[116:119], v[212:215], v[220:223], v[116:119]
	v_mfma_f32_16x16x32_bf16 v[108:111], v[204:207], v[228:231], v[108:111]
	v_mfma_f32_16x16x32_bf16 v[100:103], v[212:215], v[228:231], v[100:103]
	v_mfma_f32_16x16x32_bf16 v[92:95], v[204:207], v[236:239], v[92:95]
	v_mfma_f32_16x16x32_bf16 v[84:87], v[212:215], v[236:239], v[84:87]
	v_mfma_f32_16x16x32_bf16 v[76:79], v[204:207], v[244:247], v[76:79]
	v_mfma_f32_16x16x32_bf16 v[68:71], v[212:215], v[244:247], v[68:71]
	s_setprio 0
	s_barrier
; #define PG8_STAGE(bufoff, gbase, voff) do { _Pragma("unroll") for (int _i = 0; _i < 2; ++_i) \
;         __builtin_amdgcn_global_load_lds((const unsigned*)((const char*)(gbase) + (voff)[_i]), (PG8_LAS unsigned*)(lds + (bufoff) + ldsw + _i * 8192), 16, 0, 0); } while (0)
; #define PG8_LDA(dst, b, h) do { _Pragma("unroll") for (int m = 0; m < 4; ++m) _Pragma("unroll") for (int k = 0; k < 2; ++k) dst[m][k] = *(const PG8_LAS bf16x8*)(lds + PG8_SA(b, h) + aoff + m * 2048 + k * 1024); } while (0)
; #define PG8_MMA(ai, bj, At, Bt) do { __builtin_amdgcn_s_setprio(1); _Pragma("unroll") for (int m = 0; m < 4; ++m) _Pragma("unroll") for (int n = 0; n < 2; ++n) _Pragma("unroll") for (int k = 0; k < 2; ++k) \
;         acc[ai][bj][m][n] = __builtin_amdgcn_mfma_f32_16x16x32_bf16(Bt[n][k], At[m][k], acc[ai][bj][m][n], 0, 0, 0); __builtin_amdgcn_s_setprio(0); } while (0)
; #define PG8_WAIT_V(n) asm volatile("s_waitcnt vmcnt(" #n ")" ::: "memory")
; #define PG8_WAIT_L(n) asm volatile("s_waitcnt lgkmcnt(" #n ")" ::: "memory")
; #define PG8_BAR __builtin_amdgcn_s_barrier()
; #define PG8_SCHED __builtin_amdgcn_sched_barrier(0)
; template <class Epi, class Sched, bool ALIGN_EPI = false, bool SP2 = false>
; __device__ __forceinline__ void gemm_phase(PG8_LAS unsigned char* lds, const Gemm g, const Sched& S, const Epi& E) {
;     ...
;             PG8_LDA(At, 1, 1); PG8_STAGE(PG8_SB(1, 0), b3, voffB); PG8_STAGE(PG8_SB(1, 1), b3 + hstep, voffB); PG8_STAGE(PG8_SA(1, 0), a3, voffA);
;             PG8_WAIT_V(8); PG8_WAIT_L(0); PG8_BAR; PG8_MMA(1, 0, At, B0); PG8_MMA(1, 1, At, B1); PG8_BAR; PG8_SCHED;
;     ...
;         if constexpr (ALIGN_EPI) { if (wr == 0) PG8_BAR; }
	s_add_i32 s22, s63, s27
	s_mov_b32 m0, s22
	ds_read_b128 v[216:219], v155 offset:49152
	ds_read_b128 v[220:223], v155 offset:50176
	ds_read_b128 v[224:227], v155 offset:51200
	ds_read_b128 v[228:231], v155 offset:52224
	ds_read_b128 v[232:235], v155 offset:53248
	ds_read_b128 v[236:239], v155 offset:54272
	ds_read_b128 v[240:243], v155 offset:55296
	ds_read_b128 v[244:247], v155 offset:56320
	s_add_u32 vcc_lo, s20, 0x80
	s_addc_u32 vcc_hi, s21, 0
	global_load_lds_dwordx4 v2, vcc
	s_add_i32 m0, s22, 0x2000
	s_add_u32 s20, s20, 0x80080
	s_addc_u32 s21, s21, 0
	s_add_i32 s22, s64, s27
	s_add_u32 vcc_lo, s20, 0xfff80000
	s_addc_u32 vcc_hi, s21, -1
	global_load_lds_dwordx4 v0, vcc
	s_mov_b32 m0, s22
	s_nop 0
	global_load_lds_dwordx4 v2, s[20:21]
	s_add_i32 m0, s22, 0x2000
	s_nop 0
	global_load_lds_dwordx4 v0, s[20:21]
	v_lshl_add_u64 v[150:151], v[248:249], 0, s[36:37]
	s_mov_b32 m0, s35
	s_nop 0
	global_load_lds_dwordx4 v[150:151], off
	v_lshl_add_u64 v[150:151], v[250:251], 0, s[36:37]
	s_mov_b32 m0, s42
	s_nop 0
	global_load_lds_dwordx4 v[150:151], off
	s_waitcnt vmcnt(8)
	s_waitcnt lgkmcnt(0)
	s_barrier
	s_setprio 1
	s_waitcnt lgkmcnt(0)
	v_mfma_f32_16x16x32_bf16 v[64:67], v[184:187], v[216:219], v[64:67]
	v_mfma_f32_16x16x32_bf16 v[56:59], v[192:195], v[216:219], v[56:59]
	v_mfma_f32_16x16x32_bf16 v[48:51], v[184:187], v[224:227], v[48:51]
	v_mfma_f32_16x16x32_bf16 v[40:43], v[192:195], v[224:227], v[40:43]
	v_mfma_f32_16x16x32_bf16 v[32:35], v[184:187], v[232:235], v[32:35]
	v_mfma_f32_16x16x32_bf16 v[24:27], v[192:195], v[232:235], v[24:27]
	v_mfma_f32_16x16x32_bf16 v[16:19], v[184:187], v[240:243], v[16:19]
	v_mfma_f32_16x16x32_bf16 v[8:11], v[192:195], v[240:243], v[8:11]
	v_mfma_f32_16x16x32_bf16 v[64:67], v[188:191], v[220:223], v[64:67]
	v_mfma_f32_16x16x32_bf16 v[56:59], v[196:199], v[220:223], v[56:59]
	v_mfma_f32_16x16x32_bf16 v[48:51], v[188:191], v[228:231], v[48:51]
	v_mfma_f32_16x16x32_bf16 v[40:43], v[196:199], v[228:231], v[40:43]
	v_mfma_f32_16x16x32_bf16 v[32:35], v[188:191], v[236:239], v[32:35]
	v_mfma_f32_16x16x32_bf16 v[24:27], v[196:199], v[236:239], v[24:27]
	v_mfma_f32_16x16x32_bf16 v[16:19], v[188:191], v[244:247], v[16:19]
	v_mfma_f32_16x16x32_bf16 v[8:11], v[196:199], v[244:247], v[8:11]
	s_setprio 0
	s_setprio 1
	v_mfma_f32_16x16x32_bf16 v[60:63], v[200:203], v[216:219], v[60:63]
	v_mfma_f32_16x16x32_bf16 v[52:55], v[208:211], v[216:219], v[52:55]
	v_mfma_f32_16x16x32_bf16 v[44:47], v[200:203], v[224:227], v[44:47]
	v_mfma_f32_16x16x32_bf16 v[36:39], v[208:211], v[224:227], v[36:39]
	v_mfma_f32_16x16x32_bf16 v[28:31], v[200:203], v[232:235], v[28:31]
	v_mfma_f32_16x16x32_bf16 v[20:23], v[208:211], v[232:235], v[20:23]
	v_mfma_f32_16x16x32_bf16 v[12:15], v[200:203], v[240:243], v[12:15]
	v_mfma_f32_16x16x32_bf16 v[4:7], v[208:211], v[240:243], v[4:7]
	v_mfma_f32_16x16x32_bf16 v[60:63], v[204:207], v[220:223], v[60:63]
	v_mfma_f32_16x16x32_bf16 v[52:55], v[212:215], v[220:223], v[52:55]
	v_mfma_f32_16x16x32_bf16 v[44:47], v[204:207], v[228:231], v[44:47]
	v_mfma_f32_16x16x32_bf16 v[36:39], v[212:215], v[228:231], v[36:39]
	v_mfma_f32_16x16x32_bf16 v[28:31], v[204:207], v[236:239], v[28:31]
	v_mfma_f32_16x16x32_bf16 v[20:23], v[212:215], v[236:239], v[20:23]
	v_mfma_f32_16x16x32_bf16 v[12:15], v[204:207], v[244:247], v[12:15]
	v_mfma_f32_16x16x32_bf16 v[4:7], v[212:215], v[244:247], v[4:7]
	s_setprio 0
	s_barrier
	s_add_i32 s57, s57, 2
	s_add_u32 s18, s18, 0x100
	s_addc_u32 s19, s19, 0
	s_add_u32 s51, s51, 0x100
	s_addc_u32 s56, s56, 0
	s_cmp_gt_u32 s57, 29
	s_cbranch_scc0 .LBB0_567
	s_and_b64 vcc, exec, s[6:7]
	s_cbranch_vccz .LBB0_570
	s_barrier
